# scan: Q''/K'' operand images by LDS-DMA (XOR-swizzled 16-byte chunks), K''^T fragments of the next chunk prefetched into registers
# speedup vs baseline: 1.0015x; 1.0015x over previous
; #define LAS __attribute__((address_space(3)))
; __device__ void scan_phase(LAS unsigned char* lds, const Params& p) {
;     const int tid = threadIdx.x, w = __builtin_amdgcn_readfirstlane(tid >> 6), lane = tid & 63, ln = lane & 15, lq = lane >> 4;
;     constexpr int QST = 136, VST = 36;
;     constexpr int OFF_KS = 17408, OFF_V = 34816, BUFB = 39424;
;     LAS bf16_t* Sr = (LAS bf16_t*)(lds + 2 * BUFB);
;     LAS float* scs = (LAS float*)(lds + 2 * BUFB + 9216);
;     bf16_t* O = (bf16_t*)p.out;
;     bf16_t* Odummy = (bf16_t*)(p.ws + WS_A) + (size_t)blockIdx.x * 64 * 512;
;     const float* RT = (const float*)(p.ws + WS_RT);
;     const int eb = w & 1, tb = w >> 1;
;     if (w >= 4) __builtin_amdgcn_s_setprio(1);
;     for (int item = blockIdx.x; item < 256; item += gridDim.x) {
;         const int seq = (item & 7) + 8 * (item >> 5), es = (item >> 3) & 3;
;         const int dir = seq & 1, h = (seq >> 1) & 3, b = seq >> 3;
;         const char* Qx = (const char*)((const bf16_t*)(p.ws + (dir ? WS_QB : WS_QF)) + h * 128);
;         const char* Kx = (const char*)((const bf16_t*)(p.ws + (dir ? WS_KB : WS_KF)) + h * 128);
;         const char* Vx = (const char*)((const bf16_t*)(p.ws + WS_V) + h * 128 + es * 32);
;         const char* Rx = (const char*)(RT + (size_t)dir * NCHUNK * 512 + h * 128);
;         const char* Tx = (const char*)(RT + (size_t)(2 + dir) * NCHUNK * 512 + h * 128);
;         const unsigned qoff0 = (unsigned)((dir ? 63 - (tid >> 4) : (tid >> 4)) * 1024 + (tid & 15) * 16), qstep = dir ? (unsigned)-32768 : 32768u;
;         const unsigned voff = (unsigned)((dir ? 63 - (tid >> 3) : (tid >> 3)) * 1024 + (tid & 7) * 8), roff = (unsigned)(tid & 127) * 4u;
;         f32x4 S[2] = {(f32x4){0.f, 0.f, 0.f, 0.f}, (f32x4){0.f, 0.f, 0.f, 0.f}};
;         float tailp = 0.f;
;         u32x4 k4A[2], k4B[2], k4C[2], k4D[2]; u32x4 q4A[2], q4B[2], q4C[2], q4D[2]; u32x2 v4A, v4B, v4C, v4D; float rvA, tlA, rvB, tlB, rvC, tlC, rvD, tlD;
.LBB0_256:
	s_cmp_lt_i32 s72, 4
	s_cselect_b64 s[8:9], -1, 0
	s_waitcnt lgkmcnt(0)
	s_and_b64 s[38:39], s[8:9], s[6:7]
	s_andn2_b64 vcc, exec, s[38:39]
	s_cbranch_vccnz .LBB0_308
	v_lshrrev_b32_e32 v1, 6, v0
	s_nop 0
	v_readfirstlane_b32 s6, v1
	s_lshr_b32 s7, s6, 1
	s_and_b32 s8, s6, 1
	s_mov_b32 s9, s2
	s_load_dword s35, s[0:1], 0x98
	s_cmp_ge_u32 s7, 2
	s_cselect_b32 s11, 1, 0
	s_cmp_le_u32 s8, s7
	s_cselect_b32 s13, 1, 0
	s_add_u32 s3, s8, 2
	s_cmp_le_u32 s3, s7
	s_cselect_b32 s14, 1, 0
	v_and_b32_e32 v58, 15, v0
	v_bfe_u32 v59, v0, 4, 2
	v_lshrrev_b32_e32 v90, 2, v58
	v_and_b32_e32 v91, 3, v0
	v_and_b32_e32 v92, 63, v0
	v_lshlrev_b32_e32 v93, 2, v59
	v_add_u32_e32 v1, 0, v93
	v_cmp_le_u32_e64 s[94:95], v1, v58
	v_add_u32_e32 v1, 1, v93
	v_cmp_le_u32_e64 s[96:97], v1, v58
	v_add_u32_e32 v1, 2, v93
	v_cmp_le_u32_e64 s[98:99], v1, v58
	v_add_u32_e32 v1, 3, v93
	v_cmp_le_u32_e64 vcc, v1, v58
	s_cmp_eq_u32 s8, s7
	s_cselect_b64 s[76:77], s[94:95], -1
	s_cselect_b64 s[78:79], s[96:97], -1
	s_cselect_b64 s[80:81], s[98:99], -1
	s_cselect_b64 s[82:83], vcc, -1
	s_cmp_eq_u32 s13, 0
	s_cselect_b64 s[76:77], 0, s[76:77]
	s_cselect_b64 s[78:79], 0, s[78:79]
	s_cselect_b64 s[80:81], 0, s[80:81]
	s_cselect_b64 s[82:83], 0, s[82:83]
	s_add_u32 s3, s8, 2
	s_cmp_eq_u32 s3, s7
	s_cselect_b64 s[84:85], s[94:95], -1
	s_cselect_b64 s[88:89], s[96:97], -1
	s_cselect_b64 s[90:91], s[98:99], -1
	s_cselect_b64 s[92:93], vcc, -1
	s_lshl_b32 s12, s6, 10
	v_lshrrev_b32_e32 v1, 3, v0
	v_mul_u32_u24_e32 v63, 72, v1
	v_and_b32_e32 v1, 7, v0
	v_lshl_add_u32 v63, v1, 3, v63
	v_and_b32_e32 v1, 0x7f, v0
	v_lshlrev_b32_e32 v56, 2, v1
	s_cmp_lt_u32 s6, 2
	s_mov_b32 s4, 121344
	s_cselect_b32 s3, s4, 122880
	v_add_u32_e32 v78, s3, v56
	s_lshl_b32 s3, s7, 7
	s_add_u32 s3, s3, 121344
	v_lshl_add_u32 v79, v58, 2, s3
	s_mul_i32 s3, s7, 2304
	s_lshl_b32 s4, s8, 5
	s_add_u32 s3, s3, s4
	v_mul_u32_u24_e32 v1, 72, v58
	v_lshl_add_u32 v1, v59, 3, v1
	v_add_u32_e32 v1, s3, v1
	v_add_u32_e32 v80, 112128, v1
	v_add_u32_e32 v81, 131088, v1
	v_lshrrev_b32_e32 v93, 4, v0
	v_bfe_u32 v1, v93, 3, 1
	v_bfe_u32 v94, v93, 2, 1
	v_xor_b32_e32 v94, v1, v94
	v_lshl_or_b32 v94, v94, 3, v1
	v_and_b32_e32 v1, 3, v93
	v_lshl_or_b32 v94, v1, 1, v94
	v_xor_b32_e32 v94, v58, v94
	v_bfe_u32 v1, v58, 3, 1
	v_bfe_u32 v93, v58, 2, 1
	v_xor_b32_e32 v93, v1, v93
	v_lshl_or_b32 v93, v93, 3, v1
	v_and_b32_e32 v1, 3, v58
	v_lshl_or_b32 v93, v1, 1, v93
	v_xor_b32_e32 v93, v59, v93
	s_lshl_b32 s3, s7, 12
	s_lshl_b32 s4, s8, 12
	s_add_u32 s4, s4, 16384
	v_xor_b32_e32 v1, 0, v93
	v_lshlrev_b32_e32 v1, 4, v1
	v_lshl_add_u32 v1, v58, 8, v1
	v_add_u32_e32 v14, s3, v1
	v_add_u32_e32 v26, s4, v1
	v_add_u32_e32 v18, 32768, v14
	v_add_u32_e32 v30, 32768, v26
	v_add_u32_e32 v22, 65536, v14
	v_add_u32_e32 v34, 65536, v26
	v_xor_b32_e32 v1, 4, v93
	v_lshlrev_b32_e32 v1, 4, v1
	v_lshl_add_u32 v1, v58, 8, v1
	v_add_u32_e32 v15, s3, v1
	v_add_u32_e32 v27, s4, v1
	v_add_u32_e32 v19, 32768, v15
	v_add_u32_e32 v31, 32768, v27
	v_add_u32_e32 v23, 65536, v15
	v_add_u32_e32 v35, 65536, v27
	v_xor_b32_e32 v1, 8, v93
	v_lshlrev_b32_e32 v1, 4, v1
	v_lshl_add_u32 v1, v58, 8, v1
	v_add_u32_e32 v16, s3, v1
	v_add_u32_e32 v28, s4, v1
	v_add_u32_e32 v20, 32768, v16
	v_add_u32_e32 v32, 32768, v28
	v_add_u32_e32 v24, 65536, v16
	v_add_u32_e32 v36, 65536, v28
	v_xor_b32_e32 v1, 12, v93
	v_lshlrev_b32_e32 v1, 4, v1
	v_lshl_add_u32 v1, v58, 8, v1
	v_add_u32_e32 v17, s3, v1
	v_add_u32_e32 v29, s4, v1
	v_add_u32_e32 v21, 32768, v17
	v_add_u32_e32 v33, 32768, v29
	v_add_u32_e32 v25, 65536, v17
	v_add_u32_e32 v37, 65536, v29
	s_lshl_b32 s3, s7, 11
	v_lshl_add_u32 v1, v92, 4, s3
	s_lshl_b32 s4, s8, 3
	v_add_u32_e32 v86, 140304, v1
	v_add_u32_e32 v84, s4, v86
	v_add_u32_e32 v87, 148496, v1
	v_add_u32_e32 v85, s4, v87
	v_lshl_add_u32 v1, v59, 3, v90
	v_mul_u32_u24_e32 v1, 72, v1
	v_lshl_add_u32 v1, v91, 3, v1
	s_lshl_b32 s4, s8, 5
	v_add_u32_e32 v1, s4, v1
	v_add_u32_e32 v82, 112128, v1
	v_add_u32_e32 v83, 131088, v1
	v_lshl_add_u32 v1, v59, 2, v90
	v_mul_u32_u24_e32 v72, 72, v1
	v_lshl_add_u32 v72, v91, 3, v72
	v_add_u32_e32 v72, s4, v72
	v_lshl_add_u32 v93, v59, 2, v90
	v_bfe_u32 v1, v93, 3, 1
	v_bfe_u32 v92, v93, 2, 1
	v_xor_b32_e32 v92, v1, v92
	v_lshl_or_b32 v92, v92, 3, v1
	v_and_b32_e32 v1, 3, v93
	v_lshl_or_b32 v92, v1, 1, v92
	v_lshrrev_b32_e32 v1, 1, v91
	s_lshl_b32 s3, s7, 2
	v_add_u32_e32 v1, s3, v1
	v_xor_b32_e32 v92, v1, v92
	v_and_b32_e32 v1, 1, v91
	v_lshlrev_b32_e32 v1, 3, v1
	v_lshl_add_u32 v1, v93, 8, v1
	v_add_u32_e32 v1, 16384, v1
	v_lshl_add_u32 v38, v92, 4, v1
	v_xor_b32_e32 v92, 2, v92
	v_lshl_add_u32 v39, v92, 4, v1
	v_add_u32_e32 v40, 32768, v38
	v_add_u32_e32 v41, 32768, v39
	v_add_u32_e32 v180, 65536, v38
	v_add_u32_e32 v181, 65536, v39
	v_add_u32_e32 v65, 107520, v63
	v_add_u32_e32 v64, 102912, v63
	v_add_u32_e32 v63, 98304, v63
	v_add_u32_e32 v74, 107520, v72
	v_add_u32_e32 v73, 102912, v72
	v_add_u32_e32 v72, 98304, v72
	s_waitcnt lgkmcnt(0)
	s_cmp_gt_u32 s9, 0xff
	s_cbranch_scc1 .Lsc5_done
; #define SCAN_BAR() asm volatile("s_waitcnt lgkmcnt(0)\n\ts_barrier" ::: "memory")
; __device__ void scan_phase(LAS unsigned char* lds, const Params& p) {
;     ...
;     for (int item = blockIdx.x; item < 256; item += gridDim.x) {
;         const int seq = (item & 7) + 8 * (item >> 5), es = (item >> 3) & 3;
;         const int dir = seq & 1, h = (seq >> 1) & 3, b = seq >> 3;
;         const char* Qx = (const char*)((const bf16_t*)(p.ws + (dir ? WS_QB : WS_QF)) + h * 128);
;         const char* Kx = (const char*)((const bf16_t*)(p.ws + (dir ? WS_KB : WS_KF)) + h * 128);
;         const char* Vx = (const char*)((const bf16_t*)(p.ws + WS_V) + h * 128 + es * 32);
;         const char* Rx = (const char*)(RT + (size_t)dir * NCHUNK * 512 + h * 128);
;         const char* Tx = (const char*)(RT + (size_t)(2 + dir) * NCHUNK * 512 + h * 128);
;         const unsigned qoff0 = (unsigned)((dir ? 63 - (tid >> 4) : (tid >> 4)) * 1024 + (tid & 15) * 16), qstep = dir ? (unsigned)-32768 : 32768u;
;         const unsigned voff = (unsigned)((dir ? 63 - (tid >> 3) : (tid >> 3)) * 1024 + (tid & 7) * 8), roff = (unsigned)(tid & 127) * 4u;
;         f32x4 S[2] = {(f32x4){0.f, 0.f, 0.f, 0.f}, (f32x4){0.f, 0.f, 0.f, 0.f}};
;         float tailp = 0.f;
;         u32x4 k4A[2], k4B[2], k4C[2], k4D[2]; u32x4 q4A[2], q4B[2], q4C[2], q4D[2]; u32x2 v4A, v4B, v4C, v4D; float rvA, tlA, rvB, tlB, rvC, tlC, rvD, tlD;
;     ...
;         SCAN_LOAD(0, k4A, q4A, v4A, rvA, tlA); SCAN_LOAD(1, k4B, q4B, v4B, rvB, tlB); SCAN_LOAD(2, k4C, q4C, v4C, rvC, tlC); SCAN_LOAD(3, k4D, q4D, v4D, rvD, tlD);
;         SCAN_STAGE(0, k4A, q4A, v4A, rvA, tlA); SCAN_LOAD(4, k4A, q4A, v4A, rvA, tlA);
;         SCAN_BAR();
.Lsc5_item:
	s_and_b32 s10, s9, 1
	s_lshr_b32 s3, s9, 1
	s_and_b32 s3, s3, 3
	s_lshr_b32 s4, s9, 5
	s_lshr_b32 s5, s9, 3
	s_and_b32 s5, s5, 3
	s_cmp_eq_u32 s10, 0
	s_cselect_b32 s15, 1, -1
	s_cselect_b32 s64, 0, 3
	s_cselect_b32 s65, -4, 0x43
	s_lshl_b32 s16, s4, 2
	s_add_u32 s16, s16, 0x200
	s_lshl_b32 s17, s4, 6
	s_add_u32 s16, s16, s64
	s_add_i32 s17, s17, s65
	s_lshl_b32 s3, s3, 8
	s_lshl_b32 s5, s5, 6
	s_cmp_eq_u32 s10, 0
	s_mov_b32 s65, 0x5100000
	s_cselect_b32 s64, s65, 0x7300000
	s_add_u32 s64, s64, s3
	s_add_u32 s18, s70, s64
	s_addc_u32 s19, s71, 0
	s_cmp_eq_u32 s10, 0
	s_mov_b32 s65, 0x9500000
	s_cselect_b32 s64, s65, 0xb700000
	s_add_u32 s64, s64, s3
	s_add_u32 s20, s70, s64
	s_addc_u32 s21, s71, 0
	s_add_u32 s64, s3, s5
	s_add_u32 s65, s64, 0xd900000
	s_add_u32 s22, s70, s65
	s_addc_u32 s23, s71, 0
	s_lshl_b32 s65, s10, 25
	s_add_u32 s64, s64, s65
	s_add_u32 s28, s68, s64
	s_addc_u32 s29, s69, 0
	s_mul_i32 s64, s10, 0x110000
	s_lshl_b32 s65, s3, 1
	s_add_u32 s64, s64, s65
	s_add_u32 s64, s64, 0x15b00000
	s_add_u32 s24, s70, s64
	s_addc_u32 s25, s71, 0
	s_add_u32 s26, s24, 0x220000
	s_addc_u32 s27, s25, 0
	s_lshl_b32 s64, s9, 16
	s_add_u32 s64, s64, 0xd00000
	s_add_u32 s30, s70, s64
	s_addc_u32 s31, s71, 0
	s_mul_i32 s5, s10, 63
	s_lshl_b32 s3, s7, 4
	v_add_u32_e32 v1, s3, v58
	v_xor_b32_e32 v1, s5, v1
	v_lshlrev_b32_e32 v1, 10, v1
	s_lshl_b32 s3, s8, 5
	v_lshl_add_u32 v57, v59, 3, v1
	v_add_u32_e32 v57, s3, v57
	v_lshrrev_b32_e32 v1, 4, v0
	v_xor_b32_e32 v93, s5, v1
	v_lshlrev_b32_e32 v93, 10, v93
	v_lshl_add_u32 v53, v94, 4, v93
	v_add_u32_e32 v1, 32, v1
	v_xor_b32_e32 v93, s5, v1
	v_lshlrev_b32_e32 v93, 10, v93
	v_lshl_add_u32 v54, v94, 4, v93
	v_lshrrev_b32_e32 v1, 3, v0
	v_xor_b32_e32 v1, s5, v1
	v_lshlrev_b32_e32 v1, 10, v1
	v_and_b32_e32 v93, 7, v0
	v_lshl_add_u32 v55, v93, 3, v1
	v_mov_b32_e32 v42, 0
	v_mov_b32_e32 v43, 0
	v_mov_b32_e32 v44, 0
	v_mov_b32_e32 v45, 0
	v_mov_b32_e32 v46, 0
	v_mov_b32_e32 v47, 0
	v_mov_b32_e32 v48, 0
	v_mov_b32_e32 v49, 0
	v_mov_b32_e32 v52, 0
	v_mov_b32_e32 v160, 0
	v_mov_b32_e32 v161, 0
	v_mov_b32_e32 v162, 0
	v_mov_b32_e32 v163, 0
	v_mov_b32_e32 v176, 0
	v_mov_b32_e32 v177, 0
	s_mov_b32 s3, 0
	s_cmp_lt_u32 s3, 4
	s_cselect_b32 s4, s16, s17
	s_mul_i32 s5, s3, s15
	s_add_i32 s4, s4, s5
	s_lshl_b32 s5, s4, 16
	s_lshl_b32 s4, s4, 11
	s_add_u32 s44, s22, s5
	s_addc_u32 s45, s23, 0
	s_add_u32 s46, s24, s4
	s_addc_u32 s47, s25, 0
	s_add_u32 s50, s26, s4
	s_addc_u32 s51, s27, 0
	global_load_dwordx2 v[2:3], v55, s[44:45]
	global_load_dword v4, v56, s[46:47]
	global_load_dword v5, v56, s[50:51]
	s_mov_b32 s3, 1
	s_cmp_lt_u32 s3, 4
	s_cselect_b32 s4, s16, s17
	s_mul_i32 s5, s3, s15
	s_add_i32 s4, s4, s5
	s_lshl_b32 s5, s4, 16
	s_lshl_b32 s4, s4, 11
	s_add_u32 s44, s22, s5
	s_addc_u32 s45, s23, 0
	s_add_u32 s46, s24, s4
	s_addc_u32 s47, s25, 0
	s_add_u32 s50, s26, s4
	s_addc_u32 s51, s27, 0
	global_load_dwordx2 v[6:7], v55, s[44:45]
	global_load_dword v8, v56, s[46:47]
	global_load_dword v9, v56, s[50:51]
	s_mov_b32 s3, 0
	s_cmp_lt_u32 s3, 4
	s_cselect_b32 s4, s16, s17
	s_mul_i32 s5, s3, s15
	s_add_i32 s4, s4, s5
	s_lshl_b32 s5, s4, 16
	s_lshl_b32 s4, s4, 11
	s_add_u32 s40, s18, s5
	s_addc_u32 s41, s19, 0
	s_add_u32 s42, s20, s5
	s_addc_u32 s43, s21, 0
	s_add_u32 m0, s12, 0
	s_nop 0
	global_load_lds_dwordx4 v53, s[40:41]
	s_add_u32 m0, s12, 8192
	s_nop 0
	global_load_lds_dwordx4 v54, s[40:41]
	s_add_u32 m0, s12, 16384
	s_nop 0
	global_load_lds_dwordx4 v53, s[42:43]
	s_add_u32 m0, s12, 24576
	s_nop 0
	global_load_lds_dwordx4 v54, s[42:43]
	s_mov_b32 s3, 1
	s_cmp_lt_u32 s3, 4
	s_cselect_b32 s4, s16, s17
	s_mul_i32 s5, s3, s15
	s_add_i32 s4, s4, s5
	s_lshl_b32 s5, s4, 16
	s_lshl_b32 s4, s4, 11
	s_add_u32 s40, s18, s5
	s_addc_u32 s41, s19, 0
	s_add_u32 s42, s20, s5
	s_addc_u32 s43, s21, 0
	s_add_u32 m0, s12, 32768
	s_nop 0
	global_load_lds_dwordx4 v53, s[40:41]
	s_add_u32 m0, s12, 40960
	s_nop 0
	global_load_lds_dwordx4 v54, s[40:41]
	s_add_u32 m0, s12, 49152
	s_nop 0
	global_load_lds_dwordx4 v53, s[42:43]
	s_add_u32 m0, s12, 57344
	s_nop 0
	global_load_lds_dwordx4 v54, s[42:43]
	s_waitcnt vmcnt(0)
	ds_write_b64 v63, v[2:3]
	v_add_f32_e32 v92, v4, v52
	v_mul_f32_e32 v92, 0x3fb8aa3b, v92
	v_exp_f32_e32 v92, v92
	v_mov_b32_e32 v52, v5
	ds_write_b32 v78, v92 offset:0
	ds_write_b64 v64, v[6:7]
	v_add_f32_e32 v92, v8, v52
	v_mul_f32_e32 v92, 0x3fb8aa3b, v92
	v_exp_f32_e32 v92, v92
	v_mov_b32_e32 v52, v9
	ds_write_b32 v78, v92 offset:512
	s_mov_b32 s3, 2
	s_cmp_lt_u32 s3, 4
	s_cselect_b32 s4, s16, s17
	s_mul_i32 s5, s3, s15
	s_add_i32 s4, s4, s5
	s_lshl_b32 s5, s4, 16
	s_lshl_b32 s4, s4, 11
	s_add_u32 s44, s22, s5
	s_addc_u32 s45, s23, 0
	s_add_u32 s46, s24, s4
	s_addc_u32 s47, s25, 0
	s_add_u32 s50, s26, s4
	s_addc_u32 s51, s27, 0
	global_load_dwordx2 v[10:11], v55, s[44:45]
	global_load_dword v12, v56, s[46:47]
	global_load_dword v13, v56, s[50:51]
	global_store_dwordx2 v57, v[176:177], s[30:31]
	s_mov_b32 s3, 2
	s_cmp_lt_u32 s3, 4
	s_cselect_b32 s4, s16, s17
	s_mul_i32 s5, s3, s15
	s_add_i32 s4, s4, s5
	s_lshl_b32 s5, s4, 16
	s_lshl_b32 s4, s4, 11
	s_add_u32 s40, s18, s5
	s_addc_u32 s41, s19, 0
	s_add_u32 s42, s20, s5
	s_addc_u32 s43, s21, 0
	s_add_u32 m0, s12, 65536
	s_nop 0
	global_load_lds_dwordx4 v53, s[40:41]
	s_add_u32 m0, s12, 73728
	s_nop 0
	global_load_lds_dwordx4 v54, s[40:41]
	s_add_u32 m0, s12, 81920
	s_nop 0
	global_load_lds_dwordx4 v53, s[42:43]
	s_add_u32 m0, s12, 90112
	s_nop 0
	global_load_lds_dwordx4 v54, s[42:43]
	s_mov_b32 s3, 3
	s_cmp_lt_u32 s3, 4
	s_cselect_b32 s4, s16, s17
	s_mul_i32 s5, s3, s15
	s_add_i32 s4, s4, s5
	s_lshl_b32 s5, s4, 16
	s_lshl_b32 s4, s4, 11
	s_add_u32 s44, s22, s5
	s_addc_u32 s45, s23, 0
	s_add_u32 s46, s24, s4
	s_addc_u32 s47, s25, 0
	s_add_u32 s50, s26, s4
	s_addc_u32 s51, s27, 0
	global_load_dwordx2 v[2:3], v55, s[44:45]
	global_load_dword v4, v56, s[46:47]
	global_load_dword v5, v56, s[50:51]
	global_store_dwordx2 v57, v[176:177], s[30:31]
	s_waitcnt lgkmcnt(0)
	s_barrier
	ds_read_b32 v50, v79 offset:0
	ds_read_b32 v51, v79 offset:64
	ds_read_b128 v[96:99], v14
	ds_read_b128 v[100:103], v15
	ds_read_b128 v[104:107], v16
	ds_read_b128 v[108:111], v17
	ds_read_b128 v[216:219], v26
	ds_read_b128 v[220:223], v27
	ds_read_b128 v[224:227], v28
	ds_read_b128 v[228:231], v29
	s_waitcnt lgkmcnt(0)
	ds_read_b64_tr_b16 v[136:137], v38 offset:0
	ds_read_b64_tr_b16 v[138:139], v38 offset:4096
	ds_read_b64_tr_b16 v[140:141], v39 offset:0
	ds_read_b64_tr_b16 v[142:143], v39 offset:4096
	ds_read_b64_tr_b16 v[144:145], v38 offset:8192
	ds_read_b64_tr_b16 v[146:147], v38 offset:12288
	ds_read_b64_tr_b16 v[148:149], v39 offset:8192
	ds_read_b64_tr_b16 v[150:151], v39 offset:12288
	s_cmp_eq_u32 s14, 0
	s_cbranch_scc1 .Lsc5_noy_p
	ds_read_b128 v[232:235], v26 offset:8192
	ds_read_b128 v[236:239], v27 offset:8192
	ds_read_b128 v[240:243], v28 offset:8192
	ds_read_b128 v[244:247], v29 offset:8192

; #define SCAN_BAR() asm volatile("s_waitcnt lgkmcnt(0)\n\ts_barrier" ::: "memory")
; __device__ void scan_phase(LAS unsigned char* lds, const Params& p) {
;     ...
;         SCAN_LOAD(0, k4A, q4A, v4A, rvA, tlA); SCAN_LOAD(1, k4B, q4B, v4B, rvB, tlB); SCAN_LOAD(2, k4C, q4C, v4C, rvC, tlC); SCAN_LOAD(3, k4D, q4D, v4D, rvD, tlD);
;         SCAN_STAGE(0, k4A, q4A, v4A, rvA, tlA); SCAN_LOAD(4, k4A, q4A, v4A, rvA, tlA);
;         SCAN_BAR();
; #pragma unroll 1
;         for (int n0 = 0; n0 < 68; n0 += 4) {
;             SCAN_STAGE(1, k4B, q4B, v4B, rvB, tlB); SCAN_LOAD(min(n0 + 5, 67), k4B, q4B, v4B, rvB, tlB); SCAN_MAT(0, n0); SCAN_BAR();
;             SCAN_STAGE(0, k4C, q4C, v4C, rvC, tlC); SCAN_LOAD(min(n0 + 6, 67), k4C, q4C, v4C, rvC, tlC); SCAN_MAT(1, n0 + 1); SCAN_BAR();
;             SCAN_STAGE(1, k4D, q4D, v4D, rvD, tlD); SCAN_LOAD(min(n0 + 7, 67), k4D, q4D, v4D, rvD, tlD); SCAN_MAT(0, n0 + 2); SCAN_BAR();
;             SCAN_STAGE(0, k4A, q4A, v4A, rvA, tlA); SCAN_LOAD(min(n0 + 8, 67), k4A, q4A, v4A, rvA, tlA); SCAN_MAT(1, n0 + 3); SCAN_BAR();
.Lsc5_loop:
	ds_read_b32 v50, v79 offset:512
	ds_read_b32 v51, v79 offset:576
	ds_read_b64_tr_b16 v[128:129], v72 offset:0
	ds_read_b64_tr_b16 v[130:131], v72 offset:1152
	ds_read_b64_tr_b16 v[132:133], v72 offset:2304
	ds_read_b64_tr_b16 v[134:135], v72 offset:3456
	ds_read_b64_tr_b16 v[112:113], v82 offset:0
	ds_read_b64_tr_b16 v[114:115], v82 offset:288
	ds_read_b64_tr_b16 v[116:117], v82 offset:2304
	ds_read_b64_tr_b16 v[118:119], v82 offset:2592
	ds_read_b64_tr_b16 v[120:121], v82 offset:4608
	ds_read_b64_tr_b16 v[122:123], v82 offset:4896
	ds_read_b64_tr_b16 v[124:125], v82 offset:6912
	ds_read_b64_tr_b16 v[126:127], v82 offset:7200
	s_add_u32 s3, s34, 3
	s_min_u32 s3, s3, 67
	s_cmp_lt_u32 s3, 4
	s_cselect_b32 s4, s16, s17
	s_mul_i32 s5, s3, s15
	s_add_i32 s4, s4, s5
	s_lshl_b32 s5, s4, 16
	s_lshl_b32 s4, s4, 11
	s_add_u32 s40, s18, s5
	s_addc_u32 s41, s19, 0
	s_add_u32 s42, s20, s5
	s_addc_u32 s43, s21, 0
	s_add_u32 m0, s12, 0
	s_nop 0
	global_load_lds_dwordx4 v53, s[40:41]
	s_add_u32 m0, s12, 8192
	s_nop 0
	global_load_lds_dwordx4 v54, s[40:41]
	s_add_u32 m0, s12, 16384
	s_nop 0
	global_load_lds_dwordx4 v53, s[42:43]
	s_add_u32 m0, s12, 24576
	s_nop 0
	global_load_lds_dwordx4 v54, s[42:43]
	s_add_u32 s3, s34, 4
	s_min_u32 s3, s3, 67
	s_cmp_lt_u32 s3, 4
	s_cselect_b32 s4, s16, s17
	s_mul_i32 s5, s3, s15
	s_add_i32 s4, s4, s5
	s_lshl_b32 s5, s4, 16
	s_lshl_b32 s4, s4, 11
	s_add_u32 s44, s22, s5
	s_addc_u32 s45, s23, 0
	s_add_u32 s46, s24, s4
	s_addc_u32 s47, s25, 0
	s_add_u32 s50, s26, s4
	s_addc_u32 s51, s27, 0
	global_load_dwordx2 v[6:7], v55, s[44:45]
	global_load_dword v8, v56, s[46:47]
	global_load_dword v9, v56, s[50:51]
	s_waitcnt lgkmcnt(8)
	v_mfma_f32_16x16x32_bf16 v[42:45], v[128:131], v[136:139], v[42:45]
	ds_read_b128 v[164:167], v86
	ds_read_b128 v[168:171], v86 offset:1024
	v_mfma_f32_16x16x32_bf16 v[46:49], v[128:131], v[140:143], v[46:49]
	ds_read_b128 v[200:203], v18
	ds_read_b128 v[204:207], v19
	v_mfma_f32_16x16x32_bf16 v[42:45], v[132:135], v[144:147], v[42:45]
	ds_read_b128 v[208:211], v20
	ds_read_b128 v[212:215], v21
	v_mfma_f32_16x16x32_bf16 v[46:49], v[132:135], v[148:151], v[46:49]
	s_waitcnt lgkmcnt(12)
	v_mfma_f32_16x16x32_bf16 v[172:175], v[112:115], v[96:99], 0
	s_waitcnt vmcnt(16)
	ds_write_b64 v65, v[10:11]
	v_add_f32_e32 v92, v12, v52
	v_mul_f32_e32 v92, 0x3fb8aa3b, v92
	v_exp_f32_e32 v92, v92
	v_mov_b32_e32 v52, v13
	ds_write_b32 v78, v92 offset:1024
	s_waitcnt lgkmcnt(12)
	v_mfma_f32_16x16x32_bf16 v[172:175], v[116:119], v[100:103], v[172:175]
	ds_read_b128 v[216:219], v30
	ds_read_b128 v[220:223], v31
	s_waitcnt lgkmcnt(12)
	v_mfma_f32_16x16x32_bf16 v[172:175], v[120:123], v[104:107], v[172:175]
	ds_read_b128 v[224:227], v32
	ds_read_b128 v[228:231], v33
	s_waitcnt lgkmcnt(12)
	v_mfma_f32_16x16x32_bf16 v[172:175], v[124:127], v[108:111], v[172:175]
	ds_read_b64_tr_b16 v[188:189], v40 offset:0
	ds_read_b64_tr_b16 v[190:191], v40 offset:4096
	s_waitcnt lgkmcnt(13)
	v_mfma_f32_16x16x32_bf16 v[172:175], v[128:131], v[164:167], v[172:175]
	ds_read_b64_tr_b16 v[192:193], v41 offset:0
	ds_read_b64_tr_b16 v[194:195], v41 offset:4096
	s_waitcnt lgkmcnt(14)
	s_cmp_eq_u32 s11, 0
	s_cbranch_scc1 .Lsc5_nopv1_0
	v_mfma_f32_16x16x32_bf16 v[172:175], v[132:135], v[168:171], v[172:175]
.Lsc5_nopv1_0:
	s_waitcnt lgkmcnt(10)
	ds_read_b64_tr_b16 v[196:197], v40 offset:8192
	ds_read_b64_tr_b16 v[198:199], v40 offset:12288
	ds_read_b64_tr_b16 v[248:249], v41 offset:8192
	ds_read_b64_tr_b16 v[250:251], v41 offset:12288
	s_waitcnt lgkmcnt(8)
	v_mfma_f32_16x16x32_bf16 v[152:155], v[216:219], v[200:203], 0
	v_mfma_f32_16x16x32_bf16 v[152:155], v[220:223], v[204:207], v[152:155]
	v_mfma_f32_16x16x32_bf16 v[152:155], v[224:227], v[208:211], v[152:155]
	v_mfma_f32_16x16x32_bf16 v[152:155], v[228:231], v[212:215], v[152:155]
	s_cmp_eq_u32 s14, 0
	s_cbranch_scc1 .Lsc5_noy_0
	ds_read_b128 v[232:235], v30 offset:8192
	ds_read_b128 v[236:239], v31 offset:8192
	ds_read_b128 v[240:243], v32 offset:8192
	ds_read_b128 v[244:247], v33 offset:8192
.Lsc5_noy_0:
	v_mul_f32_e32 v42, v42, v50
	v_mul_f32_e32 v43, v43, v50
	v_mul_f32_e32 v44, v44, v50
	v_mul_f32_e32 v45, v45, v50
	v_mul_f32_e32 v46, v46, v51
	v_mul_f32_e32 v47, v47, v51
	v_mul_f32_e32 v48, v48, v51
	v_mul_f32_e32 v49, v49, v51
	v_cvt_pk_bf16_f32 v88, v42, v43
	v_cvt_pk_bf16_f32 v89, v44, v45
	v_cvt_pk_bf16_f32 v90, v46, v47
	v_cvt_pk_bf16_f32 v91, v48, v49
	ds_write_b64 v81, v[88:89]
	ds_write_b64 v81, v[90:91] offset:1152
	s_add_u32 s3, s34, 0
	s_cmp_lt_u32 s3, 4
	s_cselect_b32 s4, s16, s17
	s_mul_i32 s5, s3, s15
	s_add_i32 s4, s4, s5
	s_lshl_b32 s4, s4, 16
	s_add_u32 s64, s28, s4
	s_addc_u32 s65, s29, 0
	s_cmp_eq_u32 s34, 0
	s_cselect_b32 s64, s30, s64
	s_cselect_b32 s65, s31, s65
	v_cvt_pk_bf16_f32 v176, v172, v173
	v_cvt_pk_bf16_f32 v177, v174, v175
	s_waitcnt lgkmcnt(0)
	s_cmp_eq_u32 s14, 0
	s_cbranch_scc1 .Lsc5_noy2_0
	v_mfma_f32_16x16x32_bf16 v[156:159], v[232:235], v[200:203], 0
	v_mfma_f32_16x16x32_bf16 v[156:159], v[236:239], v[204:207], v[156:159]
	v_mfma_f32_16x16x32_bf16 v[156:159], v[240:243], v[208:211], v[156:159]
	v_mfma_f32_16x16x32_bf16 v[156:159], v[244:247], v[212:215], v[156:159]

; #define SCAN_BAR() asm volatile("s_waitcnt lgkmcnt(0)\n\ts_barrier" ::: "memory")
; __device__ void scan_phase(LAS unsigned char* lds, const Params& p) {
;     ...
;         SCAN_LOAD(0, k4A, q4A, v4A, rvA, tlA); SCAN_LOAD(1, k4B, q4B, v4B, rvB, tlB); SCAN_LOAD(2, k4C, q4C, v4C, rvC, tlC); SCAN_LOAD(3, k4D, q4D, v4D, rvD, tlD);
;         SCAN_STAGE(0, k4A, q4A, v4A, rvA, tlA); SCAN_LOAD(4, k4A, q4A, v4A, rvA, tlA);
;         SCAN_BAR();
; #pragma unroll 1
;         for (int n0 = 0; n0 < 68; n0 += 4) {
;             SCAN_STAGE(1, k4B, q4B, v4B, rvB, tlB); SCAN_LOAD(min(n0 + 5, 67), k4B, q4B, v4B, rvB, tlB); SCAN_MAT(0, n0); SCAN_BAR();
;             SCAN_STAGE(0, k4C, q4C, v4C, rvC, tlC); SCAN_LOAD(min(n0 + 6, 67), k4C, q4C, v4C, rvC, tlC); SCAN_MAT(1, n0 + 1); SCAN_BAR();
;             SCAN_STAGE(1, k4D, q4D, v4D, rvD, tlD); SCAN_LOAD(min(n0 + 7, 67), k4D, q4D, v4D, rvD, tlD); SCAN_MAT(0, n0 + 2); SCAN_BAR();
;             SCAN_STAGE(0, k4A, q4A, v4A, rvA, tlA); SCAN_LOAD(min(n0 + 8, 67), k4A, q4A, v4A, rvA, tlA); SCAN_MAT(1, n0 + 3); SCAN_BAR();
.Lsc5_noy3_0:
	ds_write_b64 v85, v[160:161]
	ds_write_b64 v85, v[162:163] offset:1024
	s_waitcnt vmcnt(12)
	s_waitcnt lgkmcnt(0)
	s_barrier
	ds_read_b32 v50, v79 offset:1024
	ds_read_b32 v51, v79 offset:1088
	ds_read_b64_tr_b16 v[128:129], v73 offset:0
	ds_read_b64_tr_b16 v[130:131], v73 offset:1152
	ds_read_b64_tr_b16 v[132:133], v73 offset:2304
	ds_read_b64_tr_b16 v[134:135], v73 offset:3456
	ds_read_b64_tr_b16 v[112:113], v83 offset:0
	ds_read_b64_tr_b16 v[114:115], v83 offset:288
	ds_read_b64_tr_b16 v[116:117], v83 offset:2304
	ds_read_b64_tr_b16 v[118:119], v83 offset:2592
	ds_read_b64_tr_b16 v[120:121], v83 offset:4608
	ds_read_b64_tr_b16 v[122:123], v83 offset:4896
	ds_read_b64_tr_b16 v[124:125], v83 offset:6912
	ds_read_b64_tr_b16 v[126:127], v83 offset:7200
	s_add_u32 s3, s34, 4
	s_min_u32 s3, s3, 67
	s_cmp_lt_u32 s3, 4
	s_cselect_b32 s4, s16, s17
	s_mul_i32 s5, s3, s15
	s_add_i32 s4, s4, s5
	s_lshl_b32 s5, s4, 16
	s_lshl_b32 s4, s4, 11
	s_add_u32 s40, s18, s5
	s_addc_u32 s41, s19, 0
	s_add_u32 s42, s20, s5
	s_addc_u32 s43, s21, 0
	s_add_u32 m0, s12, 32768
	s_nop 0
	global_load_lds_dwordx4 v53, s[40:41]
	s_add_u32 m0, s12, 40960
	s_nop 0
	global_load_lds_dwordx4 v54, s[40:41]
	s_add_u32 m0, s12, 49152
	s_nop 0
	global_load_lds_dwordx4 v53, s[42:43]
	s_add_u32 m0, s12, 57344
	s_nop 0
	global_load_lds_dwordx4 v54, s[42:43]
	s_add_u32 s3, s34, 5
	s_min_u32 s3, s3, 67
	s_cmp_lt_u32 s3, 4
	s_cselect_b32 s4, s16, s17
	s_mul_i32 s5, s3, s15
	s_add_i32 s4, s4, s5
	s_lshl_b32 s5, s4, 16
	s_lshl_b32 s4, s4, 11
	s_add_u32 s44, s22, s5
	s_addc_u32 s45, s23, 0
	s_add_u32 s46, s24, s4
	s_addc_u32 s47, s25, 0
	s_add_u32 s50, s26, s4
	s_addc_u32 s51, s27, 0
	global_load_dwordx2 v[10:11], v55, s[44:45]
	global_load_dword v12, v56, s[46:47]
	global_load_dword v13, v56, s[50:51]
	s_waitcnt lgkmcnt(8)
	v_mfma_f32_16x16x32_bf16 v[42:45], v[128:131], v[188:191], v[42:45]
	ds_read_b128 v[164:167], v87
	ds_read_b128 v[168:171], v87 offset:1024
	v_mfma_f32_16x16x32_bf16 v[46:49], v[128:131], v[192:195], v[46:49]
	ds_read_b128 v[96:99], v22
	ds_read_b128 v[100:103], v23
	v_mfma_f32_16x16x32_bf16 v[42:45], v[132:135], v[196:199], v[42:45]
	ds_read_b128 v[104:107], v24
	ds_read_b128 v[108:111], v25
	v_mfma_f32_16x16x32_bf16 v[46:49], v[132:135], v[248:251], v[46:49]
	s_waitcnt lgkmcnt(12)
	v_mfma_f32_16x16x32_bf16 v[172:175], v[112:115], v[200:203], 0
	s_waitcnt vmcnt(16)
	ds_write_b64 v63, v[2:3]
	v_add_f32_e32 v92, v4, v52
	v_mul_f32_e32 v92, 0x3fb8aa3b, v92
	v_exp_f32_e32 v92, v92
	v_mov_b32_e32 v52, v5
	ds_write_b32 v78, v92 offset:0
	s_waitcnt lgkmcnt(12)
	v_mfma_f32_16x16x32_bf16 v[172:175], v[116:119], v[204:207], v[172:175]
	ds_read_b128 v[216:219], v34
	ds_read_b128 v[220:223], v35
	s_waitcnt lgkmcnt(12)
	v_mfma_f32_16x16x32_bf16 v[172:175], v[120:123], v[208:211], v[172:175]
	ds_read_b128 v[224:227], v36
	ds_read_b128 v[228:231], v37
	s_waitcnt lgkmcnt(12)
	v_mfma_f32_16x16x32_bf16 v[172:175], v[124:127], v[212:215], v[172:175]
	ds_read_b64_tr_b16 v[136:137], v180 offset:0
	ds_read_b64_tr_b16 v[138:139], v180 offset:4096
	s_waitcnt lgkmcnt(13)
	v_mfma_f32_16x16x32_bf16 v[172:175], v[128:131], v[164:167], v[172:175]
	ds_read_b64_tr_b16 v[140:141], v181 offset:0
	ds_read_b64_tr_b16 v[142:143], v181 offset:4096
	s_waitcnt lgkmcnt(14)
	s_cmp_eq_u32 s11, 0
	s_cbranch_scc1 .Lsc5_nopv1_1
	v_mfma_f32_16x16x32_bf16 v[172:175], v[132:135], v[168:171], v[172:175]
.Lsc5_nopv1_1:
	s_waitcnt lgkmcnt(10)
	ds_read_b64_tr_b16 v[144:145], v180 offset:8192
	ds_read_b64_tr_b16 v[146:147], v180 offset:12288
	ds_read_b64_tr_b16 v[148:149], v181 offset:8192
	ds_read_b64_tr_b16 v[150:151], v181 offset:12288
	s_waitcnt lgkmcnt(8)
	v_mfma_f32_16x16x32_bf16 v[152:155], v[216:219], v[96:99], 0
	v_mfma_f32_16x16x32_bf16 v[152:155], v[220:223], v[100:103], v[152:155]
	v_mfma_f32_16x16x32_bf16 v[152:155], v[224:227], v[104:107], v[152:155]
	v_mfma_f32_16x16x32_bf16 v[152:155], v[228:231], v[108:111], v[152:155]
	s_cmp_eq_u32 s14, 0
	s_cbranch_scc1 .Lsc5_noy_1
	ds_read_b128 v[232:235], v34 offset:8192
	ds_read_b128 v[236:239], v35 offset:8192
	ds_read_b128 v[240:243], v36 offset:8192
	ds_read_b128 v[244:247], v37 offset:8192
.Lsc5_noy_1:
	v_mul_f32_e32 v42, v42, v50
	v_mul_f32_e32 v43, v43, v50
	v_mul_f32_e32 v44, v44, v50
	v_mul_f32_e32 v45, v45, v50
	v_mul_f32_e32 v46, v46, v51
	v_mul_f32_e32 v47, v47, v51
	v_mul_f32_e32 v48, v48, v51
	v_mul_f32_e32 v49, v49, v51
	v_cvt_pk_bf16_f32 v88, v42, v43
	v_cvt_pk_bf16_f32 v89, v44, v45
	v_cvt_pk_bf16_f32 v90, v46, v47
	v_cvt_pk_bf16_f32 v91, v48, v49
	ds_write_b64 v80, v[88:89]
	ds_write_b64 v80, v[90:91] offset:1152
	s_add_u32 s3, s34, 1
	s_cmp_lt_u32 s3, 4
	s_cselect_b32 s4, s16, s17
	s_mul_i32 s5, s3, s15
	s_add_i32 s4, s4, s5
	s_lshl_b32 s4, s4, 16
	s_add_u32 s64, s28, s4
	s_addc_u32 s65, s29, 0
	s_cmp_eq_u32 s34, 0
	s_cselect_b32 s64, s30, s64
	s_cselect_b32 s65, s31, s65
	v_cvt_pk_bf16_f32 v176, v172, v173
	v_cvt_pk_bf16_f32 v177, v174, v175
	s_waitcnt lgkmcnt(0)
	s_cmp_eq_u32 s14, 0
	s_cbranch_scc1 .Lsc5_noy2_1
	v_mfma_f32_16x16x32_bf16 v[156:159], v[232:235], v[96:99], 0
	v_mfma_f32_16x16x32_bf16 v[156:159], v[236:239], v[100:103], v[156:159]
	v_mfma_f32_16x16x32_bf16 v[156:159], v[240:243], v[104:107], v[156:159]
	v_mfma_f32_16x16x32_bf16 v[156:159], v[244:247], v[108:111], v[156:159]

; #define SCAN_BAR() asm volatile("s_waitcnt lgkmcnt(0)\n\ts_barrier" ::: "memory")
; __device__ void scan_phase(LAS unsigned char* lds, const Params& p) {
;     ...
;         SCAN_LOAD(0, k4A, q4A, v4A, rvA, tlA); SCAN_LOAD(1, k4B, q4B, v4B, rvB, tlB); SCAN_LOAD(2, k4C, q4C, v4C, rvC, tlC); SCAN_LOAD(3, k4D, q4D, v4D, rvD, tlD);
;         SCAN_STAGE(0, k4A, q4A, v4A, rvA, tlA); SCAN_LOAD(4, k4A, q4A, v4A, rvA, tlA);
;         SCAN_BAR();
; #pragma unroll 1
;         for (int n0 = 0; n0 < 68; n0 += 4) {
;             SCAN_STAGE(1, k4B, q4B, v4B, rvB, tlB); SCAN_LOAD(min(n0 + 5, 67), k4B, q4B, v4B, rvB, tlB); SCAN_MAT(0, n0); SCAN_BAR();
;             SCAN_STAGE(0, k4C, q4C, v4C, rvC, tlC); SCAN_LOAD(min(n0 + 6, 67), k4C, q4C, v4C, rvC, tlC); SCAN_MAT(1, n0 + 1); SCAN_BAR();
;             SCAN_STAGE(1, k4D, q4D, v4D, rvD, tlD); SCAN_LOAD(min(n0 + 7, 67), k4D, q4D, v4D, rvD, tlD); SCAN_MAT(0, n0 + 2); SCAN_BAR();
;             SCAN_STAGE(0, k4A, q4A, v4A, rvA, tlA); SCAN_LOAD(min(n0 + 8, 67), k4A, q4A, v4A, rvA, tlA); SCAN_MAT(1, n0 + 3); SCAN_BAR();
.Lsc5_noy3_1:
	ds_write_b64 v84, v[160:161]
	ds_write_b64 v84, v[162:163] offset:1024
	s_waitcnt vmcnt(12)
	s_waitcnt lgkmcnt(0)
	s_barrier
	ds_read_b32 v50, v79 offset:0
	ds_read_b32 v51, v79 offset:64
	ds_read_b64_tr_b16 v[128:129], v74 offset:0
	ds_read_b64_tr_b16 v[130:131], v74 offset:1152
	ds_read_b64_tr_b16 v[132:133], v74 offset:2304
	ds_read_b64_tr_b16 v[134:135], v74 offset:3456
	ds_read_b64_tr_b16 v[112:113], v82 offset:0
	ds_read_b64_tr_b16 v[114:115], v82 offset:288
	ds_read_b64_tr_b16 v[116:117], v82 offset:2304
	ds_read_b64_tr_b16 v[118:119], v82 offset:2592
	ds_read_b64_tr_b16 v[120:121], v82 offset:4608
	ds_read_b64_tr_b16 v[122:123], v82 offset:4896
	ds_read_b64_tr_b16 v[124:125], v82 offset:6912
	ds_read_b64_tr_b16 v[126:127], v82 offset:7200
	s_add_u32 s3, s34, 5
	s_min_u32 s3, s3, 67
	s_cmp_lt_u32 s3, 4
	s_cselect_b32 s4, s16, s17
	s_mul_i32 s5, s3, s15
	s_add_i32 s4, s4, s5
	s_lshl_b32 s5, s4, 16
	s_lshl_b32 s4, s4, 11
	s_add_u32 s40, s18, s5
	s_addc_u32 s41, s19, 0
	s_add_u32 s42, s20, s5
	s_addc_u32 s43, s21, 0
	s_add_u32 m0, s12, 65536
	s_nop 0
	global_load_lds_dwordx4 v53, s[40:41]
	s_add_u32 m0, s12, 73728
	s_nop 0
	global_load_lds_dwordx4 v54, s[40:41]
	s_add_u32 m0, s12, 81920
	s_nop 0
	global_load_lds_dwordx4 v53, s[42:43]
	s_add_u32 m0, s12, 90112
	s_nop 0
	global_load_lds_dwordx4 v54, s[42:43]
	s_add_u32 s3, s34, 6
	s_min_u32 s3, s3, 67
	s_cmp_lt_u32 s3, 4
	s_cselect_b32 s4, s16, s17
	s_mul_i32 s5, s3, s15
	s_add_i32 s4, s4, s5
	s_lshl_b32 s5, s4, 16
	s_lshl_b32 s4, s4, 11
	s_add_u32 s44, s22, s5
	s_addc_u32 s45, s23, 0
	s_add_u32 s46, s24, s4
	s_addc_u32 s47, s25, 0
	s_add_u32 s50, s26, s4
	s_addc_u32 s51, s27, 0
	global_load_dwordx2 v[2:3], v55, s[44:45]
	global_load_dword v4, v56, s[46:47]
	global_load_dword v5, v56, s[50:51]
	s_waitcnt lgkmcnt(8)
	v_mfma_f32_16x16x32_bf16 v[42:45], v[128:131], v[136:139], v[42:45]
	ds_read_b128 v[164:167], v86
	ds_read_b128 v[168:171], v86 offset:1024
	v_mfma_f32_16x16x32_bf16 v[46:49], v[128:131], v[140:143], v[46:49]
	ds_read_b128 v[200:203], v14
	ds_read_b128 v[204:207], v15
	v_mfma_f32_16x16x32_bf16 v[42:45], v[132:135], v[144:147], v[42:45]
	ds_read_b128 v[208:211], v16
	ds_read_b128 v[212:215], v17
	v_mfma_f32_16x16x32_bf16 v[46:49], v[132:135], v[148:151], v[46:49]
	s_waitcnt lgkmcnt(12)
	v_mfma_f32_16x16x32_bf16 v[172:175], v[112:115], v[96:99], 0
	s_waitcnt vmcnt(16)
	ds_write_b64 v64, v[6:7]
	v_add_f32_e32 v92, v8, v52
	v_mul_f32_e32 v92, 0x3fb8aa3b, v92
	v_exp_f32_e32 v92, v92
	v_mov_b32_e32 v52, v9
	ds_write_b32 v78, v92 offset:512
	s_waitcnt lgkmcnt(12)
	v_mfma_f32_16x16x32_bf16 v[172:175], v[116:119], v[100:103], v[172:175]
	ds_read_b128 v[216:219], v26
	ds_read_b128 v[220:223], v27
	s_waitcnt lgkmcnt(12)
	v_mfma_f32_16x16x32_bf16 v[172:175], v[120:123], v[104:107], v[172:175]
	ds_read_b128 v[224:227], v28
	ds_read_b128 v[228:231], v29
	s_waitcnt lgkmcnt(12)
	v_mfma_f32_16x16x32_bf16 v[172:175], v[124:127], v[108:111], v[172:175]
	ds_read_b64_tr_b16 v[188:189], v38 offset:0
	ds_read_b64_tr_b16 v[190:191], v38 offset:4096
	s_waitcnt lgkmcnt(13)
	v_mfma_f32_16x16x32_bf16 v[172:175], v[128:131], v[164:167], v[172:175]
	ds_read_b64_tr_b16 v[192:193], v39 offset:0
	ds_read_b64_tr_b16 v[194:195], v39 offset:4096
	s_waitcnt lgkmcnt(14)
	s_cmp_eq_u32 s11, 0
	s_cbranch_scc1 .Lsc5_nopv1_2
	v_mfma_f32_16x16x32_bf16 v[172:175], v[132:135], v[168:171], v[172:175]
.Lsc5_nopv1_2:
	s_waitcnt lgkmcnt(10)
	ds_read_b64_tr_b16 v[196:197], v38 offset:8192
	ds_read_b64_tr_b16 v[198:199], v38 offset:12288
	ds_read_b64_tr_b16 v[248:249], v39 offset:8192
	ds_read_b64_tr_b16 v[250:251], v39 offset:12288
	s_waitcnt lgkmcnt(8)
	v_mfma_f32_16x16x32_bf16 v[152:155], v[216:219], v[200:203], 0
	v_mfma_f32_16x16x32_bf16 v[152:155], v[220:223], v[204:207], v[152:155]
	v_mfma_f32_16x16x32_bf16 v[152:155], v[224:227], v[208:211], v[152:155]
	v_mfma_f32_16x16x32_bf16 v[152:155], v[228:231], v[212:215], v[152:155]
	s_cmp_eq_u32 s14, 0
	s_cbranch_scc1 .Lsc5_noy_2
	ds_read_b128 v[232:235], v26 offset:8192
	ds_read_b128 v[236:239], v27 offset:8192
	ds_read_b128 v[240:243], v28 offset:8192
	ds_read_b128 v[244:247], v29 offset:8192
.Lsc5_noy_2:
	v_mul_f32_e32 v42, v42, v50
	v_mul_f32_e32 v43, v43, v50
	v_mul_f32_e32 v44, v44, v50
	v_mul_f32_e32 v45, v45, v50
	v_mul_f32_e32 v46, v46, v51
	v_mul_f32_e32 v47, v47, v51
	v_mul_f32_e32 v48, v48, v51
	v_mul_f32_e32 v49, v49, v51
	v_cvt_pk_bf16_f32 v88, v42, v43
	v_cvt_pk_bf16_f32 v89, v44, v45
	v_cvt_pk_bf16_f32 v90, v46, v47
	v_cvt_pk_bf16_f32 v91, v48, v49
	ds_write_b64 v81, v[88:89]
	ds_write_b64 v81, v[90:91] offset:1152
	s_add_u32 s3, s34, 2
	s_cmp_lt_u32 s3, 4
	s_cselect_b32 s4, s16, s17
	s_mul_i32 s5, s3, s15
	s_add_i32 s4, s4, s5
	s_lshl_b32 s4, s4, 16
	s_add_u32 s64, s28, s4
	s_addc_u32 s65, s29, 0
	s_cmp_eq_u32 s34, 0
	s_cselect_b32 s64, s30, s64
	s_cselect_b32 s65, s31, s65
	v_cvt_pk_bf16_f32 v176, v172, v173
	v_cvt_pk_bf16_f32 v177, v174, v175
	s_waitcnt lgkmcnt(0)
	s_cmp_eq_u32 s14, 0
	s_cbranch_scc1 .Lsc5_noy2_2
	v_mfma_f32_16x16x32_bf16 v[156:159], v[232:235], v[200:203], 0
	v_mfma_f32_16x16x32_bf16 v[156:159], v[236:239], v[204:207], v[156:159]
	v_mfma_f32_16x16x32_bf16 v[156:159], v[240:243], v[208:211], v[156:159]
	v_mfma_f32_16x16x32_bf16 v[156:159], v[244:247], v[212:215], v[156:159]

; #define SCAN_BAR() asm volatile("s_waitcnt lgkmcnt(0)\n\ts_barrier" ::: "memory")
; __device__ void scan_phase(LAS unsigned char* lds, const Params& p) {
;     ...
;         SCAN_LOAD(0, k4A, q4A, v4A, rvA, tlA); SCAN_LOAD(1, k4B, q4B, v4B, rvB, tlB); SCAN_LOAD(2, k4C, q4C, v4C, rvC, tlC); SCAN_LOAD(3, k4D, q4D, v4D, rvD, tlD);
;         SCAN_STAGE(0, k4A, q4A, v4A, rvA, tlA); SCAN_LOAD(4, k4A, q4A, v4A, rvA, tlA);
;         SCAN_BAR();
; #pragma unroll 1
;         for (int n0 = 0; n0 < 68; n0 += 4) {
;             SCAN_STAGE(1, k4B, q4B, v4B, rvB, tlB); SCAN_LOAD(min(n0 + 5, 67), k4B, q4B, v4B, rvB, tlB); SCAN_MAT(0, n0); SCAN_BAR();
;             SCAN_STAGE(0, k4C, q4C, v4C, rvC, tlC); SCAN_LOAD(min(n0 + 6, 67), k4C, q4C, v4C, rvC, tlC); SCAN_MAT(1, n0 + 1); SCAN_BAR();
;             SCAN_STAGE(1, k4D, q4D, v4D, rvD, tlD); SCAN_LOAD(min(n0 + 7, 67), k4D, q4D, v4D, rvD, tlD); SCAN_MAT(0, n0 + 2); SCAN_BAR();
;             SCAN_STAGE(0, k4A, q4A, v4A, rvA, tlA); SCAN_LOAD(min(n0 + 8, 67), k4A, q4A, v4A, rvA, tlA); SCAN_MAT(1, n0 + 3); SCAN_BAR();
.Lsc5_noy3_2:
	ds_write_b64 v85, v[160:161]
	ds_write_b64 v85, v[162:163] offset:1024
	s_waitcnt vmcnt(12)
	s_waitcnt lgkmcnt(0)
	s_barrier
	ds_read_b32 v50, v79 offset:512
	ds_read_b32 v51, v79 offset:576
	ds_read_b64_tr_b16 v[128:129], v72 offset:0
	ds_read_b64_tr_b16 v[130:131], v72 offset:1152
	ds_read_b64_tr_b16 v[132:133], v72 offset:2304
	ds_read_b64_tr_b16 v[134:135], v72 offset:3456
	ds_read_b64_tr_b16 v[112:113], v83 offset:0
	ds_read_b64_tr_b16 v[114:115], v83 offset:288
	ds_read_b64_tr_b16 v[116:117], v83 offset:2304
	ds_read_b64_tr_b16 v[118:119], v83 offset:2592
	ds_read_b64_tr_b16 v[120:121], v83 offset:4608
	ds_read_b64_tr_b16 v[122:123], v83 offset:4896
	ds_read_b64_tr_b16 v[124:125], v83 offset:6912
	ds_read_b64_tr_b16 v[126:127], v83 offset:7200
	s_add_u32 s3, s34, 6
	s_min_u32 s3, s3, 67
	s_cmp_lt_u32 s3, 4
	s_cselect_b32 s4, s16, s17
	s_mul_i32 s5, s3, s15
	s_add_i32 s4, s4, s5
	s_lshl_b32 s5, s4, 16
	s_lshl_b32 s4, s4, 11
	s_add_u32 s40, s18, s5
	s_addc_u32 s41, s19, 0
	s_add_u32 s42, s20, s5
	s_addc_u32 s43, s21, 0
	s_add_u32 m0, s12, 0
	s_nop 0
	global_load_lds_dwordx4 v53, s[40:41]
	s_add_u32 m0, s12, 8192
	s_nop 0
	global_load_lds_dwordx4 v54, s[40:41]
	s_add_u32 m0, s12, 16384
	s_nop 0
	global_load_lds_dwordx4 v53, s[42:43]
	s_add_u32 m0, s12, 24576
	s_nop 0
	global_load_lds_dwordx4 v54, s[42:43]
	s_add_u32 s3, s34, 7
	s_min_u32 s3, s3, 67
	s_cmp_lt_u32 s3, 4
	s_cselect_b32 s4, s16, s17
	s_mul_i32 s5, s3, s15
	s_add_i32 s4, s4, s5
	s_lshl_b32 s5, s4, 16
	s_lshl_b32 s4, s4, 11
	s_add_u32 s44, s22, s5
	s_addc_u32 s45, s23, 0
	s_add_u32 s46, s24, s4
	s_addc_u32 s47, s25, 0
	s_add_u32 s50, s26, s4
	s_addc_u32 s51, s27, 0
	global_load_dwordx2 v[6:7], v55, s[44:45]
	global_load_dword v8, v56, s[46:47]
	global_load_dword v9, v56, s[50:51]
	s_waitcnt lgkmcnt(8)
	v_mfma_f32_16x16x32_bf16 v[42:45], v[128:131], v[188:191], v[42:45]
	ds_read_b128 v[164:167], v87
	ds_read_b128 v[168:171], v87 offset:1024
	v_mfma_f32_16x16x32_bf16 v[46:49], v[128:131], v[192:195], v[46:49]
	ds_read_b128 v[96:99], v18
	ds_read_b128 v[100:103], v19
	v_mfma_f32_16x16x32_bf16 v[42:45], v[132:135], v[196:199], v[42:45]
	ds_read_b128 v[104:107], v20
	ds_read_b128 v[108:111], v21
	v_mfma_f32_16x16x32_bf16 v[46:49], v[132:135], v[248:251], v[46:49]
	s_waitcnt lgkmcnt(12)
	v_mfma_f32_16x16x32_bf16 v[172:175], v[112:115], v[200:203], 0
	s_waitcnt vmcnt(16)
	ds_write_b64 v65, v[10:11]
	v_add_f32_e32 v92, v12, v52
	v_mul_f32_e32 v92, 0x3fb8aa3b, v92
	v_exp_f32_e32 v92, v92
	v_mov_b32_e32 v52, v13
	ds_write_b32 v78, v92 offset:1024
	s_waitcnt lgkmcnt(12)
	v_mfma_f32_16x16x32_bf16 v[172:175], v[116:119], v[204:207], v[172:175]
	ds_read_b128 v[216:219], v30
	ds_read_b128 v[220:223], v31
	s_waitcnt lgkmcnt(12)
	v_mfma_f32_16x16x32_bf16 v[172:175], v[120:123], v[208:211], v[172:175]
	ds_read_b128 v[224:227], v32
	ds_read_b128 v[228:231], v33
	s_waitcnt lgkmcnt(12)
	v_mfma_f32_16x16x32_bf16 v[172:175], v[124:127], v[212:215], v[172:175]
	ds_read_b64_tr_b16 v[136:137], v40 offset:0
	ds_read_b64_tr_b16 v[138:139], v40 offset:4096
	s_waitcnt lgkmcnt(13)
	v_mfma_f32_16x16x32_bf16 v[172:175], v[128:131], v[164:167], v[172:175]
	ds_read_b64_tr_b16 v[140:141], v41 offset:0
	ds_read_b64_tr_b16 v[142:143], v41 offset:4096
	s_waitcnt lgkmcnt(14)
	s_cmp_eq_u32 s11, 0
	s_cbranch_scc1 .Lsc5_nopv1_3
	v_mfma_f32_16x16x32_bf16 v[172:175], v[132:135], v[168:171], v[172:175]
.Lsc5_nopv1_3:
	s_waitcnt lgkmcnt(10)
	ds_read_b64_tr_b16 v[144:145], v40 offset:8192
	ds_read_b64_tr_b16 v[146:147], v40 offset:12288
	ds_read_b64_tr_b16 v[148:149], v41 offset:8192
	ds_read_b64_tr_b16 v[150:151], v41 offset:12288
	s_waitcnt lgkmcnt(8)
	v_mfma_f32_16x16x32_bf16 v[152:155], v[216:219], v[96:99], 0
	v_mfma_f32_16x16x32_bf16 v[152:155], v[220:223], v[100:103], v[152:155]
	v_mfma_f32_16x16x32_bf16 v[152:155], v[224:227], v[104:107], v[152:155]
	v_mfma_f32_16x16x32_bf16 v[152:155], v[228:231], v[108:111], v[152:155]
	s_cmp_eq_u32 s14, 0
	s_cbranch_scc1 .Lsc5_noy_3
	ds_read_b128 v[232:235], v30 offset:8192
	ds_read_b128 v[236:239], v31 offset:8192
	ds_read_b128 v[240:243], v32 offset:8192
	ds_read_b128 v[244:247], v33 offset:8192
.Lsc5_noy_3:
	v_mul_f32_e32 v42, v42, v50
	v_mul_f32_e32 v43, v43, v50
	v_mul_f32_e32 v44, v44, v50
	v_mul_f32_e32 v45, v45, v50
	v_mul_f32_e32 v46, v46, v51
	v_mul_f32_e32 v47, v47, v51
	v_mul_f32_e32 v48, v48, v51
	v_mul_f32_e32 v49, v49, v51
	v_cvt_pk_bf16_f32 v88, v42, v43
	v_cvt_pk_bf16_f32 v89, v44, v45
	v_cvt_pk_bf16_f32 v90, v46, v47
	v_cvt_pk_bf16_f32 v91, v48, v49
	ds_write_b64 v80, v[88:89]
	ds_write_b64 v80, v[90:91] offset:1152
	s_add_u32 s3, s34, 3
	s_cmp_lt_u32 s3, 4
	s_cselect_b32 s4, s16, s17
	s_mul_i32 s5, s3, s15
	s_add_i32 s4, s4, s5
	s_lshl_b32 s4, s4, 16
	s_add_u32 s64, s28, s4
	s_addc_u32 s65, s29, 0
	s_cmp_eq_u32 s34, 0
	s_cselect_b32 s64, s30, s64
	s_cselect_b32 s65, s31, s65
	v_cvt_pk_bf16_f32 v176, v172, v173
	v_cvt_pk_bf16_f32 v177, v174, v175
	s_waitcnt lgkmcnt(0)
	s_cmp_eq_u32 s14, 0
	s_cbranch_scc1 .Lsc5_noy2_3
	v_mfma_f32_16x16x32_bf16 v[156:159], v[232:235], v[96:99], 0
	v_mfma_f32_16x16x32_bf16 v[156:159], v[236:239], v[100:103], v[156:159]
	v_mfma_f32_16x16x32_bf16 v[156:159], v[240:243], v[104:107], v[156:159]
	v_mfma_f32_16x16x32_bf16 v[156:159], v[244:247], v[108:111], v[156:159]

; #define SCAN_BAR() asm volatile("s_waitcnt lgkmcnt(0)\n\ts_barrier" ::: "memory")
; __device__ void scan_phase(LAS unsigned char* lds, const Params& p) {
;     ...
;         SCAN_LOAD(0, k4A, q4A, v4A, rvA, tlA); SCAN_LOAD(1, k4B, q4B, v4B, rvB, tlB); SCAN_LOAD(2, k4C, q4C, v4C, rvC, tlC); SCAN_LOAD(3, k4D, q4D, v4D, rvD, tlD);
;         SCAN_STAGE(0, k4A, q4A, v4A, rvA, tlA); SCAN_LOAD(4, k4A, q4A, v4A, rvA, tlA);
;         SCAN_BAR();
; #pragma unroll 1
;         for (int n0 = 0; n0 < 68; n0 += 4) {
;             SCAN_STAGE(1, k4B, q4B, v4B, rvB, tlB); SCAN_LOAD(min(n0 + 5, 67), k4B, q4B, v4B, rvB, tlB); SCAN_MAT(0, n0); SCAN_BAR();
;             SCAN_STAGE(0, k4C, q4C, v4C, rvC, tlC); SCAN_LOAD(min(n0 + 6, 67), k4C, q4C, v4C, rvC, tlC); SCAN_MAT(1, n0 + 1); SCAN_BAR();
;             SCAN_STAGE(1, k4D, q4D, v4D, rvD, tlD); SCAN_LOAD(min(n0 + 7, 67), k4D, q4D, v4D, rvD, tlD); SCAN_MAT(0, n0 + 2); SCAN_BAR();
;             SCAN_STAGE(0, k4A, q4A, v4A, rvA, tlA); SCAN_LOAD(min(n0 + 8, 67), k4A, q4A, v4A, rvA, tlA); SCAN_MAT(1, n0 + 3); SCAN_BAR();
.Lsc5_noy3_3:
	ds_write_b64 v84, v[160:161]
	ds_write_b64 v84, v[162:163] offset:1024
	s_waitcnt vmcnt(12)
	s_waitcnt lgkmcnt(0)
	s_barrier
	ds_read_b32 v50, v79 offset:1024
	ds_read_b32 v51, v79 offset:1088
	ds_read_b64_tr_b16 v[128:129], v73 offset:0
	ds_read_b64_tr_b16 v[130:131], v73 offset:1152
	ds_read_b64_tr_b16 v[132:133], v73 offset:2304
	ds_read_b64_tr_b16 v[134:135], v73 offset:3456
	ds_read_b64_tr_b16 v[112:113], v82 offset:0
	ds_read_b64_tr_b16 v[114:115], v82 offset:288
	ds_read_b64_tr_b16 v[116:117], v82 offset:2304
	ds_read_b64_tr_b16 v[118:119], v82 offset:2592
	ds_read_b64_tr_b16 v[120:121], v82 offset:4608
	ds_read_b64_tr_b16 v[122:123], v82 offset:4896
	ds_read_b64_tr_b16 v[124:125], v82 offset:6912
	ds_read_b64_tr_b16 v[126:127], v82 offset:7200
	s_add_u32 s3, s34, 7
	s_min_u32 s3, s3, 67
	s_cmp_lt_u32 s3, 4
	s_cselect_b32 s4, s16, s17
	s_mul_i32 s5, s3, s15
	s_add_i32 s4, s4, s5
	s_lshl_b32 s5, s4, 16
	s_lshl_b32 s4, s4, 11
	s_add_u32 s40, s18, s5
	s_addc_u32 s41, s19, 0
	s_add_u32 s42, s20, s5
	s_addc_u32 s43, s21, 0
	s_add_u32 m0, s12, 32768
	s_nop 0
	global_load_lds_dwordx4 v53, s[40:41]
	s_add_u32 m0, s12, 40960
	s_nop 0
	global_load_lds_dwordx4 v54, s[40:41]
	s_add_u32 m0, s12, 49152
	s_nop 0
	global_load_lds_dwordx4 v53, s[42:43]
	s_add_u32 m0, s12, 57344
	s_nop 0
	global_load_lds_dwordx4 v54, s[42:43]
	s_add_u32 s3, s34, 8
	s_min_u32 s3, s3, 67
	s_cmp_lt_u32 s3, 4
	s_cselect_b32 s4, s16, s17
	s_mul_i32 s5, s3, s15
	s_add_i32 s4, s4, s5
	s_lshl_b32 s5, s4, 16
	s_lshl_b32 s4, s4, 11
	s_add_u32 s44, s22, s5
	s_addc_u32 s45, s23, 0
	s_add_u32 s46, s24, s4
	s_addc_u32 s47, s25, 0
	s_add_u32 s50, s26, s4
	s_addc_u32 s51, s27, 0
	global_load_dwordx2 v[10:11], v55, s[44:45]
	global_load_dword v12, v56, s[46:47]
	global_load_dword v13, v56, s[50:51]
	s_waitcnt lgkmcnt(8)
	v_mfma_f32_16x16x32_bf16 v[42:45], v[128:131], v[136:139], v[42:45]
	ds_read_b128 v[164:167], v86
	ds_read_b128 v[168:171], v86 offset:1024
	v_mfma_f32_16x16x32_bf16 v[46:49], v[128:131], v[140:143], v[46:49]
	ds_read_b128 v[200:203], v22
	ds_read_b128 v[204:207], v23
	v_mfma_f32_16x16x32_bf16 v[42:45], v[132:135], v[144:147], v[42:45]
	ds_read_b128 v[208:211], v24
	ds_read_b128 v[212:215], v25
	v_mfma_f32_16x16x32_bf16 v[46:49], v[132:135], v[148:151], v[46:49]
	s_waitcnt lgkmcnt(12)
	v_mfma_f32_16x16x32_bf16 v[172:175], v[112:115], v[96:99], 0
	s_waitcnt vmcnt(16)
	ds_write_b64 v63, v[2:3]
	v_add_f32_e32 v92, v4, v52
	v_mul_f32_e32 v92, 0x3fb8aa3b, v92
	v_exp_f32_e32 v92, v92
	v_mov_b32_e32 v52, v5
	ds_write_b32 v78, v92 offset:0
	s_waitcnt lgkmcnt(12)
	v_mfma_f32_16x16x32_bf16 v[172:175], v[116:119], v[100:103], v[172:175]
	ds_read_b128 v[216:219], v34
	ds_read_b128 v[220:223], v35
	s_waitcnt lgkmcnt(12)
	v_mfma_f32_16x16x32_bf16 v[172:175], v[120:123], v[104:107], v[172:175]
	ds_read_b128 v[224:227], v36
	ds_read_b128 v[228:231], v37
	s_waitcnt lgkmcnt(12)
	v_mfma_f32_16x16x32_bf16 v[172:175], v[124:127], v[108:111], v[172:175]
	ds_read_b64_tr_b16 v[188:189], v180 offset:0
	ds_read_b64_tr_b16 v[190:191], v180 offset:4096
	s_waitcnt lgkmcnt(13)
	v_mfma_f32_16x16x32_bf16 v[172:175], v[128:131], v[164:167], v[172:175]
	ds_read_b64_tr_b16 v[192:193], v181 offset:0
	ds_read_b64_tr_b16 v[194:195], v181 offset:4096
	s_waitcnt lgkmcnt(14)
	s_cmp_eq_u32 s11, 0
	s_cbranch_scc1 .Lsc5_nopv1_4
	v_mfma_f32_16x16x32_bf16 v[172:175], v[132:135], v[168:171], v[172:175]
.Lsc5_nopv1_4:
	s_waitcnt lgkmcnt(10)
	ds_read_b64_tr_b16 v[196:197], v180 offset:8192
	ds_read_b64_tr_b16 v[198:199], v180 offset:12288
	ds_read_b64_tr_b16 v[248:249], v181 offset:8192
	ds_read_b64_tr_b16 v[250:251], v181 offset:12288
	s_waitcnt lgkmcnt(8)
	v_mfma_f32_16x16x32_bf16 v[152:155], v[216:219], v[200:203], 0
	v_mfma_f32_16x16x32_bf16 v[152:155], v[220:223], v[204:207], v[152:155]
	v_mfma_f32_16x16x32_bf16 v[152:155], v[224:227], v[208:211], v[152:155]
	v_mfma_f32_16x16x32_bf16 v[152:155], v[228:231], v[212:215], v[152:155]
	s_cmp_eq_u32 s14, 0
	s_cbranch_scc1 .Lsc5_noy_4
	ds_read_b128 v[232:235], v34 offset:8192
	ds_read_b128 v[236:239], v35 offset:8192
	ds_read_b128 v[240:243], v36 offset:8192
	ds_read_b128 v[244:247], v37 offset:8192
.Lsc5_noy_4:
	v_mul_f32_e32 v42, v42, v50
	v_mul_f32_e32 v43, v43, v50
	v_mul_f32_e32 v44, v44, v50
	v_mul_f32_e32 v45, v45, v50
	v_mul_f32_e32 v46, v46, v51
	v_mul_f32_e32 v47, v47, v51
	v_mul_f32_e32 v48, v48, v51
	v_mul_f32_e32 v49, v49, v51
	v_cvt_pk_bf16_f32 v88, v42, v43
	v_cvt_pk_bf16_f32 v89, v44, v45
	v_cvt_pk_bf16_f32 v90, v46, v47
	v_cvt_pk_bf16_f32 v91, v48, v49
	ds_write_b64 v81, v[88:89]
	ds_write_b64 v81, v[90:91] offset:1152
	s_add_u32 s3, s34, 4
	s_cmp_lt_u32 s3, 4
	s_cselect_b32 s4, s16, s17
	s_mul_i32 s5, s3, s15
	s_add_i32 s4, s4, s5
	s_lshl_b32 s4, s4, 16
	s_add_u32 s64, s28, s4
	s_addc_u32 s65, s29, 0
	v_cvt_pk_bf16_f32 v176, v172, v173
	v_cvt_pk_bf16_f32 v177, v174, v175
	s_waitcnt lgkmcnt(0)
	s_cmp_eq_u32 s14, 0
	s_cbranch_scc1 .Lsc5_noy2_4
	v_mfma_f32_16x16x32_bf16 v[156:159], v[232:235], v[200:203], 0
	v_mfma_f32_16x16x32_bf16 v[156:159], v[236:239], v[204:207], v[156:159]
	v_mfma_f32_16x16x32_bf16 v[156:159], v[240:243], v[208:211], v[156:159]
	v_mfma_f32_16x16x32_bf16 v[156:159], v[244:247], v[212:215], v[156:159]

.Lsc5_noy3_4:
	ds_write_b64 v85, v[160:161]
	ds_write_b64 v85, v[162:163] offset:1024
	s_waitcnt vmcnt(12)
	s_waitcnt lgkmcnt(0)
	s_barrier
	ds_read_b32 v50, v79 offset:0
	ds_read_b32 v51, v79 offset:64
	ds_read_b64_tr_b16 v[128:129], v74 offset:0
	ds_read_b64_tr_b16 v[130:131], v74 offset:1152
	ds_read_b64_tr_b16 v[132:133], v74 offset:2304
	ds_read_b64_tr_b16 v[134:135], v74 offset:3456
	ds_read_b64_tr_b16 v[112:113], v83 offset:0
	ds_read_b64_tr_b16 v[114:115], v83 offset:288
	ds_read_b64_tr_b16 v[116:117], v83 offset:2304
	ds_read_b64_tr_b16 v[118:119], v83 offset:2592
	ds_read_b64_tr_b16 v[120:121], v83 offset:4608
	ds_read_b64_tr_b16 v[122:123], v83 offset:4896
	ds_read_b64_tr_b16 v[124:125], v83 offset:6912
	ds_read_b64_tr_b16 v[126:127], v83 offset:7200
	s_add_u32 s3, s34, 8
	s_min_u32 s3, s3, 67
	s_cmp_lt_u32 s3, 4
	s_cselect_b32 s4, s16, s17
	s_mul_i32 s5, s3, s15
	s_add_i32 s4, s4, s5
	s_lshl_b32 s5, s4, 16
	s_lshl_b32 s4, s4, 11
	s_add_u32 s40, s18, s5
	s_addc_u32 s41, s19, 0
	s_add_u32 s42, s20, s5
	s_addc_u32 s43, s21, 0
	s_add_u32 m0, s12, 65536
	s_nop 0
	global_load_lds_dwordx4 v53, s[40:41]
	s_add_u32 m0, s12, 73728
	s_nop 0
	global_load_lds_dwordx4 v54, s[40:41]
	s_add_u32 m0, s12, 81920
	s_nop 0
	global_load_lds_dwordx4 v53, s[42:43]
	s_add_u32 m0, s12, 90112
	s_nop 0
	global_load_lds_dwordx4 v54, s[42:43]
	s_add_u32 s3, s34, 9
	s_min_u32 s3, s3, 67
	s_cmp_lt_u32 s3, 4
	s_cselect_b32 s4, s16, s17
	s_mul_i32 s5, s3, s15
	s_add_i32 s4, s4, s5
	s_lshl_b32 s5, s4, 16
	s_lshl_b32 s4, s4, 11
	s_add_u32 s44, s22, s5
	s_addc_u32 s45, s23, 0
	s_add_u32 s46, s24, s4
	s_addc_u32 s47, s25, 0
	s_add_u32 s50, s26, s4
	s_addc_u32 s51, s27, 0
	global_load_dwordx2 v[2:3], v55, s[44:45]
	global_load_dword v4, v56, s[46:47]
	global_load_dword v5, v56, s[50:51]
	s_waitcnt lgkmcnt(8)
	v_mfma_f32_16x16x32_bf16 v[42:45], v[128:131], v[188:191], v[42:45]
	ds_read_b128 v[164:167], v87
	ds_read_b128 v[168:171], v87 offset:1024
	v_mfma_f32_16x16x32_bf16 v[46:49], v[128:131], v[192:195], v[46:49]
	ds_read_b128 v[96:99], v14
	ds_read_b128 v[100:103], v15
	v_mfma_f32_16x16x32_bf16 v[42:45], v[132:135], v[196:199], v[42:45]
	ds_read_b128 v[104:107], v16
	ds_read_b128 v[108:111], v17
	v_mfma_f32_16x16x32_bf16 v[46:49], v[132:135], v[248:251], v[46:49]
	s_waitcnt lgkmcnt(12)
	v_mfma_f32_16x16x32_bf16 v[172:175], v[112:115], v[200:203], 0
	s_waitcnt vmcnt(16)
	ds_write_b64 v64, v[6:7]
	v_add_f32_e32 v92, v8, v52
	v_mul_f32_e32 v92, 0x3fb8aa3b, v92
	v_exp_f32_e32 v92, v92
	v_mov_b32_e32 v52, v9
	ds_write_b32 v78, v92 offset:512
	s_waitcnt lgkmcnt(12)
	v_mfma_f32_16x16x32_bf16 v[172:175], v[116:119], v[204:207], v[172:175]
	ds_read_b128 v[216:219], v26
	ds_read_b128 v[220:223], v27
	s_waitcnt lgkmcnt(12)
	v_mfma_f32_16x16x32_bf16 v[172:175], v[120:123], v[208:211], v[172:175]
	ds_read_b128 v[224:227], v28
	ds_read_b128 v[228:231], v29
	s_waitcnt lgkmcnt(12)
	v_mfma_f32_16x16x32_bf16 v[172:175], v[124:127], v[212:215], v[172:175]
	ds_read_b64_tr_b16 v[136:137], v38 offset:0
	ds_read_b64_tr_b16 v[138:139], v38 offset:4096
	s_waitcnt lgkmcnt(13)
	v_mfma_f32_16x16x32_bf16 v[172:175], v[128:131], v[164:167], v[172:175]
	ds_read_b64_tr_b16 v[140:141], v39 offset:0
	ds_read_b64_tr_b16 v[142:143], v39 offset:4096
	s_waitcnt lgkmcnt(14)
	s_cmp_eq_u32 s11, 0
	s_cbranch_scc1 .Lsc5_nopv1_5
	v_mfma_f32_16x16x32_bf16 v[172:175], v[132:135], v[168:171], v[172:175]
.Lsc5_nopv1_5:
	s_waitcnt lgkmcnt(10)
	ds_read_b64_tr_b16 v[144:145], v38 offset:8192
	ds_read_b64_tr_b16 v[146:147], v38 offset:12288
	ds_read_b64_tr_b16 v[148:149], v39 offset:8192
	ds_read_b64_tr_b16 v[150:151], v39 offset:12288
	s_waitcnt lgkmcnt(8)
	v_mfma_f32_16x16x32_bf16 v[152:155], v[216:219], v[96:99], 0
	v_mfma_f32_16x16x32_bf16 v[152:155], v[220:223], v[100:103], v[152:155]
	v_mfma_f32_16x16x32_bf16 v[152:155], v[224:227], v[104:107], v[152:155]
	v_mfma_f32_16x16x32_bf16 v[152:155], v[228:231], v[108:111], v[152:155]
	s_cmp_eq_u32 s14, 0
	s_cbranch_scc1 .Lsc5_noy_5
	ds_read_b128 v[232:235], v26 offset:8192
	ds_read_b128 v[236:239], v27 offset:8192
	ds_read_b128 v[240:243], v28 offset:8192
	ds_read_b128 v[244:247], v29 offset:8192
.Lsc5_noy_5:
	v_mul_f32_e32 v42, v42, v50
	v_mul_f32_e32 v43, v43, v50
	v_mul_f32_e32 v44, v44, v50
	v_mul_f32_e32 v45, v45, v50
	v_mul_f32_e32 v46, v46, v51
	v_mul_f32_e32 v47, v47, v51
	v_mul_f32_e32 v48, v48, v51
	v_mul_f32_e32 v49, v49, v51
	v_cvt_pk_bf16_f32 v88, v42, v43
	v_cvt_pk_bf16_f32 v89, v44, v45
	v_cvt_pk_bf16_f32 v90, v46, v47
	v_cvt_pk_bf16_f32 v91, v48, v49
	ds_write_b64 v80, v[88:89]
	ds_write_b64 v80, v[90:91] offset:1152
	s_add_u32 s3, s34, 5
	s_cmp_lt_u32 s3, 4
	s_cselect_b32 s4, s16, s17
	s_mul_i32 s5, s3, s15
	s_add_i32 s4, s4, s5
	s_lshl_b32 s4, s4, 16
	s_add_u32 s64, s28, s4
	s_addc_u32 s65, s29, 0
	v_cvt_pk_bf16_f32 v176, v172, v173
	v_cvt_pk_bf16_f32 v177, v174, v175
	s_waitcnt lgkmcnt(0)
	s_cmp_eq_u32 s14, 0
	s_cbranch_scc1 .Lsc5_noy2_5
	v_mfma_f32_16x16x32_bf16 v[156:159], v[232:235], v[96:99], 0
	v_mfma_f32_16x16x32_bf16 v[156:159], v[236:239], v[100:103], v[156:159]
	v_mfma_f32_16x16x32_bf16 v[156:159], v[240:243], v[104:107], v[156:159]
	v_mfma_f32_16x16x32_bf16 v[156:159], v[244:247], v[108:111], v[156:159]

.Lsc5_noy3_5:
	ds_write_b64 v84, v[160:161]
	ds_write_b64 v84, v[162:163] offset:1024
	s_waitcnt vmcnt(12)
	s_waitcnt lgkmcnt(0)
	s_barrier
	s_add_u32 s34, s34, 6
	s_cmp_lt_u32 s34, 66
	s_cbranch_scc1 .Lsc5_loop
	ds_read_b32 v50, v79 offset:512
	ds_read_b32 v51, v79 offset:576
	ds_read_b64_tr_b16 v[128:129], v72 offset:0
	ds_read_b64_tr_b16 v[130:131], v72 offset:1152
	ds_read_b64_tr_b16 v[132:133], v72 offset:2304
	ds_read_b64_tr_b16 v[134:135], v72 offset:3456
	ds_read_b64_tr_b16 v[112:113], v82 offset:0
	ds_read_b64_tr_b16 v[114:115], v82 offset:288
	ds_read_b64_tr_b16 v[116:117], v82 offset:2304
	ds_read_b64_tr_b16 v[118:119], v82 offset:2592
	ds_read_b64_tr_b16 v[120:121], v82 offset:4608
	ds_read_b64_tr_b16 v[122:123], v82 offset:4896
	ds_read_b64_tr_b16 v[124:125], v82 offset:6912
	ds_read_b64_tr_b16 v[126:127], v82 offset:7200
	s_add_u32 s3, s34, 3
	s_min_u32 s3, s3, 67
	s_cmp_lt_u32 s3, 4
	s_cselect_b32 s4, s16, s17
	s_mul_i32 s5, s3, s15
	s_add_i32 s4, s4, s5
	s_lshl_b32 s5, s4, 16
	s_lshl_b32 s4, s4, 11
	s_add_u32 s40, s18, s5
	s_addc_u32 s41, s19, 0
	s_add_u32 s42, s20, s5
	s_addc_u32 s43, s21, 0
	s_add_u32 m0, s12, 0
	s_nop 0
	global_load_lds_dwordx4 v53, s[40:41]
	s_add_u32 m0, s12, 8192
	s_nop 0
	global_load_lds_dwordx4 v54, s[40:41]
	s_add_u32 m0, s12, 16384
	s_nop 0
	global_load_lds_dwordx4 v53, s[42:43]
	s_add_u32 m0, s12, 24576
	s_nop 0
	global_load_lds_dwordx4 v54, s[42:43]
	s_add_u32 s3, s34, 4
	s_min_u32 s3, s3, 67
	s_cmp_lt_u32 s3, 4
	s_cselect_b32 s4, s16, s17
	s_mul_i32 s5, s3, s15
	s_add_i32 s4, s4, s5
	s_lshl_b32 s5, s4, 16
	s_lshl_b32 s4, s4, 11
	s_add_u32 s44, s22, s5
	s_addc_u32 s45, s23, 0
	s_add_u32 s46, s24, s4
	s_addc_u32 s47, s25, 0
	s_add_u32 s50, s26, s4
	s_addc_u32 s51, s27, 0
	global_load_dwordx2 v[6:7], v55, s[44:45]
	global_load_dword v8, v56, s[46:47]
	global_load_dword v9, v56, s[50:51]
	s_waitcnt lgkmcnt(8)
	v_mfma_f32_16x16x32_bf16 v[42:45], v[128:131], v[136:139], v[42:45]
	ds_read_b128 v[164:167], v86
	ds_read_b128 v[168:171], v86 offset:1024
	v_mfma_f32_16x16x32_bf16 v[46:49], v[128:131], v[140:143], v[46:49]
	ds_read_b128 v[200:203], v18
	ds_read_b128 v[204:207], v19
	v_mfma_f32_16x16x32_bf16 v[42:45], v[132:135], v[144:147], v[42:45]
	ds_read_b128 v[208:211], v20
	ds_read_b128 v[212:215], v21
	v_mfma_f32_16x16x32_bf16 v[46:49], v[132:135], v[148:151], v[46:49]
	s_waitcnt lgkmcnt(12)
	v_mfma_f32_16x16x32_bf16 v[172:175], v[112:115], v[96:99], 0
	s_waitcnt vmcnt(16)
	ds_write_b64 v65, v[10:11]
	v_add_f32_e32 v92, v12, v52
	v_mul_f32_e32 v92, 0x3fb8aa3b, v92
	v_exp_f32_e32 v92, v92
	v_mov_b32_e32 v52, v13
	ds_write_b32 v78, v92 offset:1024
	s_waitcnt lgkmcnt(12)
	v_mfma_f32_16x16x32_bf16 v[172:175], v[116:119], v[100:103], v[172:175]
	ds_read_b128 v[216:219], v30
	ds_read_b128 v[220:223], v31
	s_waitcnt lgkmcnt(12)
	v_mfma_f32_16x16x32_bf16 v[172:175], v[120:123], v[104:107], v[172:175]
	ds_read_b128 v[224:227], v32
	ds_read_b128 v[228:231], v33
	s_waitcnt lgkmcnt(12)
	v_mfma_f32_16x16x32_bf16 v[172:175], v[124:127], v[108:111], v[172:175]
	ds_read_b64_tr_b16 v[188:189], v40 offset:0
	ds_read_b64_tr_b16 v[190:191], v40 offset:4096
	s_waitcnt lgkmcnt(13)
	v_mfma_f32_16x16x32_bf16 v[172:175], v[128:131], v[164:167], v[172:175]
	ds_read_b64_tr_b16 v[192:193], v41 offset:0
	ds_read_b64_tr_b16 v[194:195], v41 offset:4096
	s_waitcnt lgkmcnt(14)
	s_cmp_eq_u32 s11, 0
	s_cbranch_scc1 .Lsc5_nopv1_t0
	v_mfma_f32_16x16x32_bf16 v[172:175], v[132:135], v[168:171], v[172:175]

.Lsc5_noy_t0:
	v_mul_f32_e32 v42, v42, v50
	v_mul_f32_e32 v43, v43, v50
	v_mul_f32_e32 v44, v44, v50
	v_mul_f32_e32 v45, v45, v50
	v_mul_f32_e32 v46, v46, v51
	v_mul_f32_e32 v47, v47, v51
	v_mul_f32_e32 v48, v48, v51
	v_mul_f32_e32 v49, v49, v51
	v_cvt_pk_bf16_f32 v88, v42, v43
	v_cvt_pk_bf16_f32 v89, v44, v45
	v_cvt_pk_bf16_f32 v90, v46, v47
	v_cvt_pk_bf16_f32 v91, v48, v49
	ds_write_b64 v81, v[88:89]
	ds_write_b64 v81, v[90:91] offset:1152
	s_add_u32 s3, s34, 0
	s_cmp_lt_u32 s3, 4
	s_cselect_b32 s4, s16, s17
	s_mul_i32 s5, s3, s15
	s_add_i32 s4, s4, s5
	s_lshl_b32 s4, s4, 16
	s_add_u32 s64, s28, s4
	s_addc_u32 s65, s29, 0
	v_cvt_pk_bf16_f32 v176, v172, v173
	v_cvt_pk_bf16_f32 v177, v174, v175
	s_waitcnt lgkmcnt(0)
	s_cmp_eq_u32 s14, 0
	s_cbranch_scc1 .Lsc5_noy2_t0
	v_mfma_f32_16x16x32_bf16 v[156:159], v[232:235], v[200:203], 0
	v_mfma_f32_16x16x32_bf16 v[156:159], v[236:239], v[204:207], v[156:159]
	v_mfma_f32_16x16x32_bf16 v[156:159], v[240:243], v[208:211], v[156:159]
	v_mfma_f32_16x16x32_bf16 v[156:159], v[244:247], v[212:215], v[156:159]

; #define SCAN_BAR() asm volatile("s_waitcnt lgkmcnt(0)\n\ts_barrier" ::: "memory")
; __device__ void scan_phase(LAS unsigned char* lds, const Params& p) {
;     ...
;         SCAN_LOAD(0, k4A, q4A, v4A, rvA, tlA); SCAN_LOAD(1, k4B, q4B, v4B, rvB, tlB); SCAN_LOAD(2, k4C, q4C, v4C, rvC, tlC); SCAN_LOAD(3, k4D, q4D, v4D, rvD, tlD);
;         SCAN_STAGE(0, k4A, q4A, v4A, rvA, tlA); SCAN_LOAD(4, k4A, q4A, v4A, rvA, tlA);
;         SCAN_BAR();
; #pragma unroll 1
;         for (int n0 = 0; n0 < 68; n0 += 4) {
;             SCAN_STAGE(1, k4B, q4B, v4B, rvB, tlB); SCAN_LOAD(min(n0 + 5, 67), k4B, q4B, v4B, rvB, tlB); SCAN_MAT(0, n0); SCAN_BAR();
;             SCAN_STAGE(0, k4C, q4C, v4C, rvC, tlC); SCAN_LOAD(min(n0 + 6, 67), k4C, q4C, v4C, rvC, tlC); SCAN_MAT(1, n0 + 1); SCAN_BAR();
;             SCAN_STAGE(1, k4D, q4D, v4D, rvD, tlD); SCAN_LOAD(min(n0 + 7, 67), k4D, q4D, v4D, rvD, tlD); SCAN_MAT(0, n0 + 2); SCAN_BAR();
;             SCAN_STAGE(0, k4A, q4A, v4A, rvA, tlA); SCAN_LOAD(min(n0 + 8, 67), k4A, q4A, v4A, rvA, tlA); SCAN_MAT(1, n0 + 3); SCAN_BAR();
;         }
.Lsc5_noy3_t0:
	ds_write_b64 v85, v[160:161]
	ds_write_b64 v85, v[162:163] offset:1024
	s_waitcnt vmcnt(12)
	s_waitcnt lgkmcnt(0)
	s_barrier
	ds_read_b64_tr_b16 v[128:129], v73 offset:0
	ds_read_b64_tr_b16 v[130:131], v73 offset:1152
	ds_read_b64_tr_b16 v[132:133], v73 offset:2304
	ds_read_b64_tr_b16 v[134:135], v73 offset:3456
	ds_read_b64_tr_b16 v[112:113], v83 offset:0
	ds_read_b64_tr_b16 v[114:115], v83 offset:288
	ds_read_b64_tr_b16 v[116:117], v83 offset:2304
	ds_read_b64_tr_b16 v[118:119], v83 offset:2592
	ds_read_b64_tr_b16 v[120:121], v83 offset:4608
	ds_read_b64_tr_b16 v[122:123], v83 offset:4896
	ds_read_b64_tr_b16 v[124:125], v83 offset:6912
	ds_read_b64_tr_b16 v[126:127], v83 offset:7200
	s_add_u32 s3, s34, 4
	s_min_u32 s3, s3, 67
	s_cmp_lt_u32 s3, 4
	s_cselect_b32 s4, s16, s17
	s_mul_i32 s5, s3, s15
	s_add_i32 s4, s4, s5
	s_lshl_b32 s5, s4, 16
	s_lshl_b32 s4, s4, 11
	s_add_u32 s40, s18, s5
	s_addc_u32 s41, s19, 0
	s_add_u32 s42, s20, s5
	s_addc_u32 s43, s21, 0
	s_add_u32 m0, s12, 32768
	s_nop 0
	global_load_lds_dwordx4 v53, s[40:41]
	s_add_u32 m0, s12, 40960
	s_nop 0
	global_load_lds_dwordx4 v54, s[40:41]
	s_add_u32 m0, s12, 49152
	s_nop 0
	global_load_lds_dwordx4 v53, s[42:43]
	s_add_u32 m0, s12, 57344
	s_nop 0
	global_load_lds_dwordx4 v54, s[42:43]
	s_add_u32 s3, s34, 5
	s_min_u32 s3, s3, 67
	s_cmp_lt_u32 s3, 4
	s_cselect_b32 s4, s16, s17
	s_mul_i32 s5, s3, s15
	s_add_i32 s4, s4, s5
	s_lshl_b32 s5, s4, 16
	s_lshl_b32 s4, s4, 11
	s_add_u32 s44, s22, s5
	s_addc_u32 s45, s23, 0
	s_add_u32 s46, s24, s4
	s_addc_u32 s47, s25, 0
	s_add_u32 s50, s26, s4
	s_addc_u32 s51, s27, 0
	global_load_dwordx2 v[10:11], v55, s[44:45]
	global_load_dword v12, v56, s[46:47]
	global_load_dword v13, v56, s[50:51]
	s_waitcnt lgkmcnt(8)
	v_mfma_f32_16x16x32_bf16 v[42:45], v[128:131], v[188:191], v[42:45]
	ds_read_b128 v[164:167], v87
	ds_read_b128 v[168:171], v87 offset:1024
	v_mfma_f32_16x16x32_bf16 v[46:49], v[128:131], v[192:195], v[46:49]
	v_mfma_f32_16x16x32_bf16 v[42:45], v[132:135], v[196:199], v[42:45]
	v_mfma_f32_16x16x32_bf16 v[46:49], v[132:135], v[248:251], v[46:49]
	s_waitcnt lgkmcnt(8)
	v_mfma_f32_16x16x32_bf16 v[172:175], v[112:115], v[200:203], 0
	s_waitcnt vmcnt(16)
	ds_write_b64 v63, v[2:3]
	v_add_f32_e32 v92, v4, v52
	v_mul_f32_e32 v92, 0x3fb8aa3b, v92
	v_exp_f32_e32 v92, v92
	v_mov_b32_e32 v52, v5
	ds_write_b32 v78, v92 offset:0
	s_waitcnt lgkmcnt(8)
	v_mfma_f32_16x16x32_bf16 v[172:175], v[116:119], v[204:207], v[172:175]
	s_waitcnt lgkmcnt(6)
	v_mfma_f32_16x16x32_bf16 v[172:175], v[120:123], v[208:211], v[172:175]
	s_waitcnt lgkmcnt(4)
	v_mfma_f32_16x16x32_bf16 v[172:175], v[124:127], v[212:215], v[172:175]
	s_waitcnt lgkmcnt(3)
	v_mfma_f32_16x16x32_bf16 v[172:175], v[128:131], v[164:167], v[172:175]
	s_waitcnt lgkmcnt(2)
	s_cmp_eq_u32 s11, 0
	s_cbranch_scc1 .Lsc5_nopv1_t1
	v_mfma_f32_16x16x32_bf16 v[172:175], v[132:135], v[168:171], v[172:175]
.Lsc5_nopv1_t1:
	s_add_u32 s3, s34, 1
	s_cmp_lt_u32 s3, 4
	s_cselect_b32 s4, s16, s17
	s_mul_i32 s5, s3, s15
	s_add_i32 s4, s4, s5
	s_lshl_b32 s4, s4, 16
	s_add_u32 s64, s28, s4
	s_addc_u32 s65, s29, 0
	s_nop 7
	v_cvt_pk_bf16_f32 v176, v172, v173
	v_cvt_pk_bf16_f32 v177, v174, v175
	global_store_dwordx2 v57, v[176:177], s[64:65]
	s_waitcnt vmcnt(12)
	s_waitcnt lgkmcnt(0)
	s_barrier
	s_add_u32 s9, s9, s35
	s_cmp_lt_u32 s9, 0x100
	s_cbranch_scc1 .Lsc5_item
